# memory-attention units: K/V^T tiles staged by LDS-DMA into three LDS buffers two tiles ahead (was global->VGPR->ds_write one tile ahead, two buffers); on top of v71
# speedup vs baseline: 1.0061x; 1.0061x over previous
.Lp2a_ok_m:
	buffer_inv sc1
	s_waitcnt vmcnt(0)
	s_add_i32 s98, s16, 0xfffffc00
	s_bfe_u32 s99, s98, 0x20004
	s_lshr_b32 s98, s98, 6
	s_lshl_b32 s100, s98, 19
	s_lshl_b32 s101, s99, 9
	s_add_i32 s100, s100, s101
	s_lshl_b32 s101, s99, 19
	s_lshl_b32 s98, s98, 9
	s_add_i32 s101, s101, s98
	v_mbcnt_lo_u32_b32 v234, -1, 0
	v_mbcnt_hi_u32_b32 v234, -1, v234
	v_add_u32_e32 v234, s83, v234
	v_mov_b32_e32 v237, 0
	v_readlane_b32 s98, v255, 41
	v_readlane_b32 s99, v255, 42
	s_nop 1
	s_add_u32 s98, s98, s100
	s_addc_u32 s99, s99, 0
	v_add_u32_e32 v235, 0, v234
	v_mul_u32_u24_e32 v238, 0xf0f1, v235
	v_lshrrev_b32_e32 v238, 20, v238
	v_mul_u32_u24_e32 v239, 17, v238
	v_sub_u32_e32 v239, v235, v239
	v_min_u32_e32 v239, 15, v239
	v_lshlrev_b32_e32 v236, 11, v238
	v_lshl_add_u32 v236, v239, 4, v236
	v_lshl_add_u64 v[194:195], v[236:237], 0, s[98:99]
	v_add_u32_e32 v235, 512, v234
	v_mul_u32_u24_e32 v238, 0xf0f1, v235
	v_lshrrev_b32_e32 v238, 20, v238
	v_mul_u32_u24_e32 v239, 17, v238
	v_sub_u32_e32 v239, v235, v239
	v_min_u32_e32 v239, 15, v239
	v_lshlrev_b32_e32 v236, 11, v238
	v_lshl_add_u32 v236, v239, 4, v236
	v_lshl_add_u64 v[196:197], v[236:237], 0, s[98:99]
	v_add_u32_e32 v235, 1024, v234
	v_min_u32_e32 v235, 0x43f, v235
	v_mul_u32_u24_e32 v238, 0xf0f1, v235
	v_lshrrev_b32_e32 v238, 20, v238
	v_mul_u32_u24_e32 v239, 17, v238
	v_sub_u32_e32 v239, v235, v239
	v_min_u32_e32 v239, 15, v239
	v_lshlrev_b32_e32 v236, 11, v238
	v_lshl_add_u32 v236, v239, 4, v236
	v_lshl_add_u64 v[198:199], v[236:237], 0, s[98:99]
	v_readlane_b32 s98, v255, 43
	v_readlane_b32 s99, v255, 44
	s_nop 1
	s_add_u32 s98, s98, s101
	s_addc_u32 s99, s99, 0
	v_add_u32_e32 v235, 0, v234
	v_mul_u32_u24_e32 v238, 0xe38f, v235
	v_lshrrev_b32_e32 v238, 19, v238
	v_mul_u32_u24_e32 v239, 9, v238
	v_sub_u32_e32 v239, v235, v239
	v_min_u32_e32 v239, 7, v239
	v_lshlrev_b32_e32 v236, 11, v238
	v_lshl_add_u32 v236, v239, 4, v236
	v_lshl_add_u64 v[222:223], v[236:237], 0, s[98:99]
	v_add_u32_e32 v235, 512, v234
	v_mul_u32_u24_e32 v238, 0xe38f, v235
	v_lshrrev_b32_e32 v238, 19, v238
	v_mul_u32_u24_e32 v239, 9, v238
	v_sub_u32_e32 v239, v235, v239
	v_min_u32_e32 v239, 7, v239
	v_lshlrev_b32_e32 v236, 11, v238
	v_lshl_add_u32 v236, v239, 4, v236
	v_lshl_add_u64 v[224:225], v[236:237], 0, s[98:99]
	v_add_u32_e32 v235, 1024, v234
	v_min_u32_e32 v235, 0x47f, v235
	v_mul_u32_u24_e32 v238, 0xe38f, v235
	v_lshrrev_b32_e32 v238, 19, v238
	v_mul_u32_u24_e32 v239, 9, v238
	v_sub_u32_e32 v239, v235, v239
	v_min_u32_e32 v239, 7, v239
	v_lshlrev_b32_e32 v236, 11, v238
	v_lshl_add_u32 v236, v239, 4, v236
	v_lshl_add_u64 v[226:227], v[236:237], 0, s[98:99]
	s_mov_b32 s98, 0x0
	s_mov_b32 s99, 0
	s_lshl_b32 s100, s83, 4
	s_add_i32 m0, s100, 0x0
	v_lshl_add_u64 v[232:233], v[194:195], 0, s[98:99]
	global_load_lds_dwordx4 v[232:233], off
	s_add_i32 m0, s100, 0x2000
	v_lshl_add_u64 v[232:233], v[196:197], 0, s[98:99]
	global_load_lds_dwordx4 v[232:233], off
	s_cmp_lt_u32 s83, 64
	s_mov_b32 s101, 0xd800
	s_cselect_b32 s101, 0x4000, s101
	s_add_i32 m0, s100, s101
	v_lshl_add_u64 v[232:233], v[198:199], 0, s[98:99]
	global_load_lds_dwordx4 v[232:233], off
	s_mov_b32 s98, 0x20000
	s_mov_b32 s99, 0
	s_lshl_b32 s100, s83, 4
	s_add_i32 m0, s100, 0x4800
	v_lshl_add_u64 v[232:233], v[194:195], 0, s[98:99]
	global_load_lds_dwordx4 v[232:233], off
	s_add_i32 m0, s100, 0x6800
	v_lshl_add_u64 v[232:233], v[196:197], 0, s[98:99]
	global_load_lds_dwordx4 v[232:233], off
	s_cmp_lt_u32 s83, 64
	s_mov_b32 s101, 0xd800
	s_cselect_b32 s101, 0x8800, s101
	s_add_i32 m0, s100, s101
	v_lshl_add_u64 v[232:233], v[198:199], 0, s[98:99]
	global_load_lds_dwordx4 v[232:233], off
	s_add_i32 s0, s16, 0xfffffc00
	s_lshr_b32 s1, s0, 6
	s_lshl_b32 s0, s16, 8
	s_and_b32 s0, s0, 0xf00
	v_readlane_b32 s5, v254, 18
	s_lshl_b32 s4, s1, 12
	s_add_i32 s0, s0, s5
	s_add_i32 s5, s0, s4
	s_lshl_b32 s0, s16, 4
	v_mbcnt_lo_u32_b32 v22, -1, 0
	v_mbcnt_hi_u32_b32 v22, -1, v22
	s_and_b32 s0, s0, 0x300
	v_add_u32_e32 v182, s83, v22
	s_lshl_b32 s4, s1, 8
	s_lshl_b32 s94, s0, 1
	v_readlane_b32 s6, v255, 41
	v_ashrrev_i32_e32 v40, 4, v182
	s_add_u32 s6, s6, s94
	v_readlane_b32 s7, v255, 42
	v_lshlrev_b32_e32 v183, 4, v22
	v_add_u32_e32 v2, s4, v40
	s_addc_u32 s7, s7, 0
	v_and_b32_e32 v0, 0xf0, v183
	v_ashrrev_i32_e32 v3, 31, v2
	v_add_u32_e32 v184, 0x200, v182
	v_lshl_add_u64 v[10:11], s[6:7], 0, v[0:1]
	v_lshlrev_b64 v[2:3], 11, v[2:3]
	v_ashrrev_i32_e32 v41, 4, v184
	v_lshl_add_u64 v[6:7], v[10:11], 0, v[2:3]
	v_add_u32_e32 v2, s4, v41
	v_ashrrev_i32_e32 v3, 31, v2
	v_lshlrev_b64 v[2:3], 11, v[2:3]
	v_lshl_add_u64 v[8:9], v[10:11], 0, v[2:3]
	v_and_b32_e32 v180, 31, v22
	v_mov_b64_e32 v[16:17], s[88:89]
	v_ashrrev_i32_e32 v181, 5, v22
	v_or_b32_e32 v158, s5, v180
	v_lshlrev_b32_e32 v18, 3, v181
	v_add_u32_e32 v0, 0, v0
	s_movk_i32 s8, 0x110
	v_mad_i64_i32 v[16:17], s[6:7], v158, s87, v[16:17]
	s_or_b32 s5, s4, 64
	v_ashrrev_i32_e32 v19, 31, v18
	v_mad_u64_u32 v[162:163], s[6:7], v40, s8, v[0:1]
	v_mad_u64_u32 v[164:165], s[6:7], v41, s8, v[0:1]
	v_lshl_add_u64 v[160:161], v[16:17], 0, s[94:95]
	v_add_u32_e32 v20, s5, v41
	v_add_u32_e32 v16, s5, v40
	v_lshl_add_u64 v[18:19], v[18:19], 1, v[160:161]
	v_ashrrev_i32_e32 v21, 31, v20
	s_mov_b64 s[6:7], 0x2000
	s_movk_i32 s5, 0x2000
	v_ashrrev_i32_e32 v17, 31, v16
	v_lshl_add_u64 v[166:167], v[18:19], 0, s[6:7]
	v_lshlrev_b64 v[20:21], 11, v[20:21]
	v_add_co_u32_e32 v18, vcc, s5, v18
	v_lshlrev_b64 v[16:17], 11, v[16:17]
	s_nop 0
	v_addc_co_u32_e32 v19, vcc, 0, v19, vcc
	v_lshl_add_u64 v[170:171], v[10:11], 0, v[20:21]
	v_lshl_add_u64 v[168:169], v[10:11], 0, v[16:17]
	v_lshlrev_b32_e32 v0, 1, v22
	v_lshrrev_b32_e32 v20, 1, v22
	v_and_b32_e32 v0, 8, v0
	v_and_b32_e32 v20, 4, v20
	v_and_b32_e32 v21, 19, v22
	v_or3_b32 v0, v0, v21, v20
	v_lshlrev_b32_e32 v36, 4, v181
	v_mul_u32_u24_e32 v20, 0x110, v0
	v_add3_u32 v165, 0, v20, v36
	v_ashrrev_i32_e32 v159, 31, v158
	v_add_u32_e32 v163, 0, v36
	s_waitcnt vmcnt(3)
	s_waitcnt lgkmcnt(0)
	s_barrier
	s_mov_b32 s98, 0x40000
	s_mov_b32 s99, 0
	s_lshl_b32 s100, s83, 4
	s_add_i32 m0, s100, 0x9000
	v_lshl_add_u64 v[232:233], v[194:195], 0, s[98:99]
	global_load_lds_dwordx4 v[232:233], off
	s_add_i32 m0, s100, 0xb000
	v_lshl_add_u64 v[232:233], v[196:197], 0, s[98:99]
	global_load_lds_dwordx4 v[232:233], off
	s_cmp_lt_u32 s83, 64
	s_mov_b32 s101, 0xd800
	s_cselect_b32 s101, 0xd000, s101
	s_add_i32 m0, s100, s101
	v_lshl_add_u64 v[232:233], v[198:199], 0, s[98:99]
	global_load_lds_dwordx4 v[232:233], off
	global_load_dwordx4 v[2:5], v[18:19], off
	global_load_dwordx4 v[154:157], v[166:167], off offset:32
	global_load_dwordx4 v[150:153], v[166:167], off offset:64
	global_load_dwordx4 v[146:149], v[166:167], off offset:96
	global_load_dwordx4 v[142:145], v[166:167], off offset:128
	global_load_dwordx4 v[138:141], v[166:167], off offset:160
	global_load_dwordx4 v[134:137], v[166:167], off offset:192
	global_load_dwordx4 v[130:133], v[166:167], off offset:224
	ds_read_b128 v[20:23], v165
	ds_read_b128 v[24:27], v165 offset:32
	ds_read_b128 v[28:31], v165 offset:8704
	ds_read_b128 v[32:35], v165 offset:8736
	s_waitcnt vmcnt(7) lgkmcnt(3)
	v_mfma_f32_32x32x16_bf16 v[114:129], v[20:23], v[2:5], 0
	v_mad_u32_u24 v0, v0, s8, v163
	s_waitcnt lgkmcnt(1)
	v_mfma_f32_32x32x16_bf16 v[82:97], v[28:31], v[2:5], 0
	s_waitcnt vmcnt(6)
	v_mfma_f32_32x32x16_bf16 v[114:129], v[24:27], v[154:157], v[114:129]
	ds_read_b128 v[20:23], v0 offset:64
	ds_read_b128 v[24:27], v0 offset:96
	ds_read_b128 v[28:31], v0 offset:8768
	ds_read_b128 v[36:39], v0 offset:8800
	s_waitcnt lgkmcnt(4)
	v_mfma_f32_32x32x16_bf16 v[82:97], v[32:35], v[154:157], v[82:97]
	s_waitcnt vmcnt(5) lgkmcnt(3)
	v_mfma_f32_32x32x16_bf16 v[114:129], v[20:23], v[150:153], v[114:129]
	s_waitcnt lgkmcnt(1)
	v_mfma_f32_32x32x16_bf16 v[82:97], v[28:31], v[150:153], v[82:97]
	s_waitcnt vmcnt(4)
	v_mfma_f32_32x32x16_bf16 v[114:129], v[24:27], v[146:149], v[114:129]
	ds_read_b128 v[20:23], v0 offset:128
	ds_read_b128 v[24:27], v0 offset:160
	ds_read_b128 v[28:31], v0 offset:8832
	ds_read_b128 v[32:35], v0 offset:8864
	s_waitcnt lgkmcnt(4)
	v_mfma_f32_32x32x16_bf16 v[82:97], v[36:39], v[146:149], v[82:97]
	s_waitcnt vmcnt(3) lgkmcnt(3)
	v_mfma_f32_32x32x16_bf16 v[114:129], v[20:23], v[142:145], v[114:129]
	s_waitcnt lgkmcnt(1)
	v_mfma_f32_32x32x16_bf16 v[82:97], v[28:31], v[142:145], v[82:97]
	s_waitcnt vmcnt(2)
	v_mfma_f32_32x32x16_bf16 v[114:129], v[24:27], v[138:141], v[114:129]
	ds_read_b128 v[20:23], v0 offset:192
	ds_read_b128 v[24:27], v0 offset:224
	ds_read_b128 v[28:31], v0 offset:8896
	ds_read_b128 v[36:39], v0 offset:8928
	s_waitcnt lgkmcnt(4)
	v_mfma_f32_32x32x16_bf16 v[82:97], v[32:35], v[138:141], v[82:97]
	s_waitcnt vmcnt(1) lgkmcnt(3)
	v_mfma_f32_32x32x16_bf16 v[114:129], v[20:23], v[134:137], v[114:129]
	s_waitcnt lgkmcnt(1)
	v_mfma_f32_32x32x16_bf16 v[82:97], v[28:31], v[134:137], v[82:97]
	s_waitcnt vmcnt(0)
	v_mfma_f32_32x32x16_bf16 v[114:129], v[24:27], v[130:133], v[114:129]
	s_waitcnt lgkmcnt(0)
	v_mfma_f32_32x32x16_bf16 v[82:97], v[36:39], v[130:133], v[82:97]
	s_or_b32 s5, s4, 0x80
	v_add_u32_e32 v12, s5, v40
	v_ashrrev_i32_e32 v13, 31, v12
	v_lshlrev_b64 v[12:13], 11, v[12:13]
	v_lshl_add_u64 v[172:173], v[10:11], 0, v[12:13]
	v_add_u32_e32 v12, s5, v41
	v_ashrrev_i32_e32 v13, 31, v12
	v_lshlrev_b64 v[12:13], 11, v[12:13]
	s_waitcnt lgkmcnt(0)
	s_barrier
	s_mov_b32 s98, 0x60000
	s_mov_b32 s99, 0
	s_lshl_b32 s100, s83, 4
	s_add_i32 m0, s100, 0x0
	v_lshl_add_u64 v[232:233], v[194:195], 0, s[98:99]
	global_load_lds_dwordx4 v[232:233], off
	s_add_i32 m0, s100, 0x2000
	v_lshl_add_u64 v[232:233], v[196:197], 0, s[98:99]
	global_load_lds_dwordx4 v[232:233], off
	s_cmp_lt_u32 s83, 64
	s_mov_b32 s101, 0xd800
	s_cselect_b32 s101, 0x4000, s101
	s_add_i32 m0, s100, s101
	v_lshl_add_u64 v[232:233], v[198:199], 0, s[98:99]
	global_load_lds_dwordx4 v[232:233], off
	v_lshl_add_u64 v[174:175], v[10:11], 0, v[12:13]
	ds_read_b128 v[20:23], v165 offset:18432
	ds_read_b128 v[24:27], v165 offset:18464
	ds_read_b128 v[28:31], v165 offset:27136
	ds_read_b128 v[32:35], v165 offset:27168
	s_waitcnt lgkmcnt(3)
	v_mfma_f32_32x32x16_bf16 v[98:113], v[20:23], v[2:5], 0
	s_waitcnt lgkmcnt(1)
	v_mfma_f32_32x32x16_bf16 v[50:65], v[28:31], v[2:5], 0
	v_mfma_f32_32x32x16_bf16 v[98:113], v[24:27], v[154:157], v[98:113]
	ds_read_b128 v[20:23], v0 offset:18496
	ds_read_b128 v[24:27], v0 offset:18528
	ds_read_b128 v[28:31], v0 offset:27200
	ds_read_b128 v[36:39], v0 offset:27232
	s_waitcnt lgkmcnt(4)
	v_mfma_f32_32x32x16_bf16 v[50:65], v[32:35], v[154:157], v[50:65]
	s_waitcnt lgkmcnt(3)
	v_mfma_f32_32x32x16_bf16 v[98:113], v[20:23], v[150:153], v[98:113]
	s_waitcnt lgkmcnt(1)
	v_mfma_f32_32x32x16_bf16 v[50:65], v[28:31], v[150:153], v[50:65]
	v_mfma_f32_32x32x16_bf16 v[98:113], v[24:27], v[146:149], v[98:113]
	ds_read_b128 v[20:23], v0 offset:18560
	ds_read_b128 v[24:27], v0 offset:18592
	ds_read_b128 v[28:31], v0 offset:27264
	ds_read_b128 v[32:35], v0 offset:27296
	s_waitcnt lgkmcnt(4)
	v_mfma_f32_32x32x16_bf16 v[50:65], v[36:39], v[146:149], v[50:65]
	s_waitcnt lgkmcnt(3)
	v_mfma_f32_32x32x16_bf16 v[98:113], v[20:23], v[142:145], v[98:113]
	s_waitcnt lgkmcnt(1)
	v_mfma_f32_32x32x16_bf16 v[50:65], v[28:31], v[142:145], v[50:65]
	v_mfma_f32_32x32x16_bf16 v[98:113], v[24:27], v[138:141], v[98:113]
	ds_read_b128 v[20:23], v0 offset:18624
	ds_read_b128 v[24:27], v0 offset:18656
	ds_read_b128 v[28:31], v0 offset:27328
	ds_read_b128 v[36:39], v0 offset:27360
	s_waitcnt lgkmcnt(4)
	v_mfma_f32_32x32x16_bf16 v[50:65], v[32:35], v[138:141], v[50:65]
	s_waitcnt lgkmcnt(3)
	v_mfma_f32_32x32x16_bf16 v[98:113], v[20:23], v[134:137], v[98:113]
	s_waitcnt lgkmcnt(1)
	v_mfma_f32_32x32x16_bf16 v[50:65], v[28:31], v[134:137], v[50:65]
	v_mfma_f32_32x32x16_bf16 v[98:113], v[24:27], v[130:133], v[98:113]
	s_waitcnt lgkmcnt(0)
	v_mfma_f32_32x32x16_bf16 v[50:65], v[36:39], v[130:133], v[50:65]
	s_or_b32 s4, s4, 0xc0
	s_waitcnt vmcnt(3)
	v_add_u32_e32 v12, s4, v40
	v_ashrrev_i32_e32 v13, 31, v12
	v_lshlrev_b64 v[12:13], 11, v[12:13]
	v_lshl_add_u64 v[176:177], v[10:11], 0, v[12:13]
	v_add_u32_e32 v12, s4, v41
	v_ashrrev_i32_e32 v13, 31, v12
	v_lshlrev_b64 v[12:13], 11, v[12:13]
	s_waitcnt lgkmcnt(0)
	s_barrier
	s_mov_b32 s98, 0x100
	s_mov_b32 s99, 0
	s_lshl_b32 s100, s83, 4
	s_add_i32 m0, s100, 0x4800
	v_lshl_add_u64 v[232:233], v[194:195], 0, s[98:99]
	global_load_lds_dwordx4 v[232:233], off
	s_add_i32 m0, s100, 0x6800
	v_lshl_add_u64 v[232:233], v[196:197], 0, s[98:99]
	global_load_lds_dwordx4 v[232:233], off
	s_cmp_lt_u32 s83, 64
	s_mov_b32 s101, 0xd800
	s_cselect_b32 s101, 0x8800, s101
	s_add_i32 m0, s100, s101
	v_lshl_add_u64 v[232:233], v[198:199], 0, s[98:99]
	global_load_lds_dwordx4 v[232:233], off
	v_lshl_add_u64 v[178:179], v[10:11], 0, v[12:13]
	ds_read_b128 v[18:21], v165 offset:36864
	ds_read_b128 v[22:25], v165 offset:36896
	ds_read_b128 v[26:29], v165 offset:45568
	ds_read_b128 v[30:33], v165 offset:45600
	s_waitcnt lgkmcnt(3)
	v_mfma_f32_32x32x16_bf16 v[66:81], v[18:21], v[2:5], 0
	s_waitcnt lgkmcnt(1)
	v_mfma_f32_32x32x16_bf16 v[34:49], v[26:29], v[2:5], 0
	v_mfma_f32_32x32x16_bf16 v[66:81], v[22:25], v[154:157], v[66:81]
	ds_read_b128 v[18:21], v0 offset:36928
	ds_read_b128 v[22:25], v0 offset:36960
	ds_read_b128 v[26:29], v0 offset:45632
	ds_read_b128 v[186:189], v0 offset:45664
	s_waitcnt lgkmcnt(4)
	v_mfma_f32_32x32x16_bf16 v[34:49], v[30:33], v[154:157], v[34:49]
	s_waitcnt lgkmcnt(3)
	v_mfma_f32_32x32x16_bf16 v[66:81], v[18:21], v[150:153], v[66:81]
	s_waitcnt lgkmcnt(1)
	v_mfma_f32_32x32x16_bf16 v[34:49], v[26:29], v[150:153], v[34:49]
	v_mfma_f32_32x32x16_bf16 v[66:81], v[22:25], v[146:149], v[66:81]
	ds_read_b128 v[18:21], v0 offset:36992
	ds_read_b128 v[22:25], v0 offset:37024
	ds_read_b128 v[26:29], v0 offset:45696
	ds_read_b128 v[30:33], v0 offset:45728
	s_waitcnt lgkmcnt(4)
	v_mfma_f32_32x32x16_bf16 v[34:49], v[186:189], v[146:149], v[34:49]
	s_waitcnt lgkmcnt(3)
	v_mfma_f32_32x32x16_bf16 v[66:81], v[18:21], v[142:145], v[66:81]
	s_waitcnt lgkmcnt(1)
	v_mfma_f32_32x32x16_bf16 v[34:49], v[26:29], v[142:145], v[34:49]
	v_mfma_f32_32x32x16_bf16 v[66:81], v[22:25], v[138:141], v[66:81]
	ds_read_b128 v[18:21], v0 offset:37056
	ds_read_b128 v[22:25], v0 offset:37088
	ds_read_b128 v[26:29], v0 offset:45760
	ds_read_b128 v[186:189], v0 offset:45792
	s_waitcnt lgkmcnt(4)
	v_mfma_f32_32x32x16_bf16 v[34:49], v[30:33], v[138:141], v[34:49]
	s_waitcnt lgkmcnt(3)
	v_mfma_f32_32x32x16_bf16 v[66:81], v[18:21], v[134:137], v[66:81]
	s_waitcnt lgkmcnt(1)
	v_mfma_f32_32x32x16_bf16 v[34:49], v[26:29], v[134:137], v[34:49]
	v_mfma_f32_32x32x16_bf16 v[66:81], v[22:25], v[130:133], v[66:81]
	s_waitcnt lgkmcnt(0)
	v_mfma_f32_32x32x16_bf16 v[34:49], v[186:189], v[130:133], v[34:49]
	s_waitcnt vmcnt(3)
	s_waitcnt lgkmcnt(0)
	s_barrier
	s_mov_b32 s98, 0x20100
	s_mov_b32 s99, 0
	s_lshl_b32 s100, s83, 4
	s_add_i32 m0, s100, 0x9000
	v_lshl_add_u64 v[232:233], v[194:195], 0, s[98:99]
	global_load_lds_dwordx4 v[232:233], off
	s_add_i32 m0, s100, 0xb000
	v_lshl_add_u64 v[232:233], v[196:197], 0, s[98:99]
	global_load_lds_dwordx4 v[232:233], off
	s_cmp_lt_u32 s83, 64
	s_mov_b32 s101, 0xd800
	s_cselect_b32 s101, 0xd000, s101
	s_add_i32 m0, s100, s101
	v_lshl_add_u64 v[232:233], v[198:199], 0, s[98:99]
	global_load_lds_dwordx4 v[232:233], off
	ds_read_b128 v[6:9], v165
	ds_read_b128 v[204:207], v165 offset:32
	ds_read_b128 v[10:13], v165 offset:8704
	ds_read_b128 v[208:211], v165 offset:8736
	s_waitcnt lgkmcnt(3)
	v_mfma_f32_32x32x16_bf16 v[18:33], v[6:9], v[2:5], 0
	s_waitcnt lgkmcnt(1)
	v_mfma_f32_32x32x16_bf16 v[2:17], v[10:13], v[2:5], 0
	v_mfma_f32_32x32x16_bf16 v[18:33], v[204:207], v[154:157], v[18:33]
	ds_read_b128 v[204:207], v0 offset:64
	ds_read_b128 v[212:215], v0 offset:96
	ds_read_b128 v[216:219], v0 offset:8768
	ds_read_b128 v[228:231], v0 offset:8800
	s_waitcnt lgkmcnt(4)
	v_mfma_f32_32x32x16_bf16 v[2:17], v[208:211], v[154:157], v[2:17]
	s_waitcnt lgkmcnt(3)
	v_mfma_f32_32x32x16_bf16 v[18:33], v[204:207], v[150:153], v[18:33]
	s_waitcnt lgkmcnt(1)
	v_mfma_f32_32x32x16_bf16 v[2:17], v[216:219], v[150:153], v[2:17]
	ds_read_b128 v[150:153], v0 offset:128
	ds_read_b128 v[154:157], v0 offset:160
	ds_read_b128 v[204:207], v0 offset:8832
	ds_read_b128 v[208:211], v0 offset:8864
	v_mfma_f32_32x32x16_bf16 v[18:33], v[212:215], v[146:149], v[18:33]
	s_waitcnt lgkmcnt(4)
	v_mfma_f32_32x32x16_bf16 v[2:17], v[228:231], v[146:149], v[2:17]
	s_waitcnt lgkmcnt(3)
	v_mfma_f32_32x32x16_bf16 v[18:33], v[150:153], v[142:145], v[18:33]
	s_waitcnt lgkmcnt(1)
	v_mfma_f32_32x32x16_bf16 v[2:17], v[204:207], v[142:145], v[2:17]
	v_mfma_f32_32x32x16_bf16 v[18:33], v[154:157], v[138:141], v[18:33]
	ds_read_b128 v[142:145], v0 offset:192
	ds_read_b128 v[146:149], v0 offset:224
	ds_read_b128 v[150:153], v0 offset:8896
	ds_read_b128 v[154:157], v0 offset:8928
	s_waitcnt lgkmcnt(4)
	v_mfma_f32_32x32x16_bf16 v[2:17], v[208:211], v[138:141], v[2:17]
	s_waitcnt lgkmcnt(3)
	v_mfma_f32_32x32x16_bf16 v[18:33], v[142:145], v[134:137], v[18:33]
	s_waitcnt lgkmcnt(1)
	v_mfma_f32_32x32x16_bf16 v[2:17], v[150:153], v[134:137], v[2:17]
	v_mfma_f32_32x32x16_bf16 v[18:33], v[146:149], v[130:133], v[18:33]
	s_waitcnt lgkmcnt(0)
	v_mfma_f32_32x32x16_bf16 v[2:17], v[154:157], v[130:133], v[2:17]
	s_waitcnt vmcnt(3)
	s_waitcnt lgkmcnt(0)
	s_barrier
	s_mov_b32 s98, 0x40100
	s_mov_b32 s99, 0
	s_lshl_b32 s100, s83, 4
	s_add_i32 m0, s100, 0x0
	v_lshl_add_u64 v[232:233], v[194:195], 0, s[98:99]
	global_load_lds_dwordx4 v[232:233], off
	s_add_i32 m0, s100, 0x2000
	v_lshl_add_u64 v[232:233], v[196:197], 0, s[98:99]
	global_load_lds_dwordx4 v[232:233], off
	s_cmp_lt_u32 s83, 64
	s_mov_b32 s101, 0xd800
	s_cselect_b32 s101, 0x4000, s101
	s_add_i32 m0, s100, s101
	v_lshl_add_u64 v[232:233], v[198:199], 0, s[98:99]
	global_load_lds_dwordx4 v[232:233], off
	s_nop 0
	s_nop 0
	global_load_dwordx4 v[186:189], v[166:167], off offset:256
	global_load_dwordx4 v[190:193], v[166:167], off offset:288
	global_load_dwordx4 v[150:153], v[166:167], off offset:320
	global_load_dwordx4 v[146:149], v[166:167], off offset:352
	global_load_dwordx4 v[142:145], v[166:167], off offset:384
	global_load_dwordx4 v[138:141], v[166:167], off offset:416
	global_load_dwordx4 v[134:137], v[166:167], off offset:448
	global_load_dwordx4 v[130:133], v[166:167], off offset:480
	ds_read_b128 v[204:207], v165 offset:18432
	ds_read_b128 v[208:211], v165 offset:18464
	ds_read_b128 v[212:215], v165 offset:27136
	ds_read_b128 v[216:219], v165 offset:27168
	s_waitcnt vmcnt(7) lgkmcnt(3)
	v_mfma_f32_32x32x16_bf16 v[114:129], v[204:207], v[186:189], v[114:129]
	s_waitcnt lgkmcnt(1)
	v_mfma_f32_32x32x16_bf16 v[82:97], v[212:215], v[186:189], v[82:97]
	s_waitcnt vmcnt(6)
	v_mfma_f32_32x32x16_bf16 v[114:129], v[208:211], v[190:193], v[114:129]
	ds_read_b128 v[204:207], v0 offset:18496
	ds_read_b128 v[208:211], v0 offset:18528
	ds_read_b128 v[212:215], v0 offset:27200
	ds_read_b128 v[228:231], v0 offset:27232
	s_waitcnt lgkmcnt(4)
	v_mfma_f32_32x32x16_bf16 v[82:97], v[216:219], v[190:193], v[82:97]
	s_waitcnt vmcnt(5) lgkmcnt(3)
	v_mfma_f32_32x32x16_bf16 v[114:129], v[204:207], v[150:153], v[114:129]
	s_waitcnt lgkmcnt(1)
	v_mfma_f32_32x32x16_bf16 v[82:97], v[212:215], v[150:153], v[82:97]
	s_waitcnt vmcnt(4)
	v_mfma_f32_32x32x16_bf16 v[114:129], v[208:211], v[146:149], v[114:129]
	ds_read_b128 v[204:207], v0 offset:18560
	ds_read_b128 v[208:211], v0 offset:18592
	ds_read_b128 v[212:215], v0 offset:27264
	ds_read_b128 v[216:219], v0 offset:27296
	s_waitcnt lgkmcnt(4)
	v_mfma_f32_32x32x16_bf16 v[82:97], v[228:231], v[146:149], v[82:97]
	s_waitcnt vmcnt(3) lgkmcnt(3)
	v_mfma_f32_32x32x16_bf16 v[114:129], v[204:207], v[142:145], v[114:129]
	s_waitcnt lgkmcnt(1)
	v_mfma_f32_32x32x16_bf16 v[82:97], v[212:215], v[142:145], v[82:97]
	s_waitcnt vmcnt(2)
	v_mfma_f32_32x32x16_bf16 v[114:129], v[208:211], v[138:141], v[114:129]
	ds_read_b128 v[204:207], v0 offset:18624
	ds_read_b128 v[208:211], v0 offset:18656
	ds_read_b128 v[212:215], v0 offset:27328
	ds_read_b128 v[228:231], v0 offset:27360
	s_waitcnt lgkmcnt(4)
	v_mfma_f32_32x32x16_bf16 v[82:97], v[216:219], v[138:141], v[82:97]
	s_waitcnt vmcnt(1) lgkmcnt(3)
	v_mfma_f32_32x32x16_bf16 v[114:129], v[204:207], v[134:137], v[114:129]
	s_waitcnt lgkmcnt(1)
	v_mfma_f32_32x32x16_bf16 v[82:97], v[212:215], v[134:137], v[82:97]
	s_waitcnt vmcnt(0)
	v_mfma_f32_32x32x16_bf16 v[114:129], v[208:211], v[130:133], v[114:129]
	s_waitcnt lgkmcnt(0)
	v_mfma_f32_32x32x16_bf16 v[82:97], v[228:231], v[130:133], v[82:97]
	s_waitcnt lgkmcnt(0)
	s_barrier
	s_mov_b32 s98, 0x60100
	s_mov_b32 s99, 0
	s_lshl_b32 s100, s83, 4
	s_add_i32 m0, s100, 0x4800
	v_lshl_add_u64 v[232:233], v[194:195], 0, s[98:99]
	global_load_lds_dwordx4 v[232:233], off
	s_add_i32 m0, s100, 0x6800
	v_lshl_add_u64 v[232:233], v[196:197], 0, s[98:99]
	global_load_lds_dwordx4 v[232:233], off
	s_cmp_lt_u32 s83, 64
	s_mov_b32 s101, 0xd800
	s_cselect_b32 s101, 0x8800, s101
	s_add_i32 m0, s100, s101
	v_lshl_add_u64 v[232:233], v[198:199], 0, s[98:99]
	global_load_lds_dwordx4 v[232:233], off
	ds_read_b128 v[170:173], v165 offset:36864
	ds_read_b128 v[204:207], v165 offset:36896
	ds_read_b128 v[208:211], v165 offset:45568
	ds_read_b128 v[212:215], v165 offset:45600
	s_waitcnt lgkmcnt(3)
	v_mfma_f32_32x32x16_bf16 v[98:113], v[170:173], v[186:189], v[98:113]
	s_waitcnt lgkmcnt(1)
	v_mfma_f32_32x32x16_bf16 v[50:65], v[208:211], v[186:189], v[50:65]
	v_mfma_f32_32x32x16_bf16 v[98:113], v[204:207], v[190:193], v[98:113]
	ds_read_b128 v[170:173], v0 offset:36928
	ds_read_b128 v[204:207], v0 offset:36960
	ds_read_b128 v[208:211], v0 offset:45632
	ds_read_b128 v[216:219], v0 offset:45664
	s_waitcnt lgkmcnt(4)
	v_mfma_f32_32x32x16_bf16 v[50:65], v[212:215], v[190:193], v[50:65]
	s_waitcnt lgkmcnt(3)
	v_mfma_f32_32x32x16_bf16 v[98:113], v[170:173], v[150:153], v[98:113]
	s_waitcnt lgkmcnt(1)
	v_mfma_f32_32x32x16_bf16 v[50:65], v[208:211], v[150:153], v[50:65]
	v_mfma_f32_32x32x16_bf16 v[98:113], v[204:207], v[146:149], v[98:113]
	ds_read_b128 v[170:173], v0 offset:36992
	ds_read_b128 v[204:207], v0 offset:37024
	ds_read_b128 v[208:211], v0 offset:45696
	ds_read_b128 v[212:215], v0 offset:45728
	s_waitcnt lgkmcnt(4)
	v_mfma_f32_32x32x16_bf16 v[50:65], v[216:219], v[146:149], v[50:65]
	s_waitcnt lgkmcnt(3)
	v_mfma_f32_32x32x16_bf16 v[98:113], v[170:173], v[142:145], v[98:113]
	s_waitcnt lgkmcnt(1)
	v_mfma_f32_32x32x16_bf16 v[50:65], v[208:211], v[142:145], v[50:65]
	v_mfma_f32_32x32x16_bf16 v[98:113], v[204:207], v[138:141], v[98:113]
	ds_read_b128 v[170:173], v0 offset:37056
	ds_read_b128 v[204:207], v0 offset:37088
	ds_read_b128 v[208:211], v0 offset:45760
	ds_read_b128 v[216:219], v0 offset:45792
	s_waitcnt lgkmcnt(4)
	v_mfma_f32_32x32x16_bf16 v[50:65], v[212:215], v[138:141], v[50:65]
	s_waitcnt lgkmcnt(3)
	v_mfma_f32_32x32x16_bf16 v[98:113], v[170:173], v[134:137], v[98:113]
	s_waitcnt lgkmcnt(1)
	v_mfma_f32_32x32x16_bf16 v[50:65], v[208:211], v[134:137], v[50:65]
	v_mfma_f32_32x32x16_bf16 v[98:113], v[204:207], v[130:133], v[98:113]
	s_waitcnt lgkmcnt(0)
	v_mfma_f32_32x32x16_bf16 v[50:65], v[216:219], v[130:133], v[50:65]
	s_waitcnt vmcnt(3)
	s_waitcnt lgkmcnt(0)
	s_barrier
	s_mov_b32 s98, 0x0
	s_mov_b32 s99, 0
	s_lshl_b32 s100, s83, 4
	s_add_i32 m0, s100, 0x9000
	v_lshl_add_u64 v[232:233], v[222:223], 0, s[98:99]
	global_load_lds_dwordx4 v[232:233], off
	s_add_i32 m0, s100, 0xb000
	v_lshl_add_u64 v[232:233], v[224:225], 0, s[98:99]
	global_load_lds_dwordx4 v[232:233], off
	s_cmp_lt_u32 s83, 128
	s_mov_b32 s101, 0xd800
	s_cselect_b32 s101, 0xd000, s101
	s_add_i32 m0, s100, s101
	v_lshl_add_u64 v[232:233], v[226:227], 0, s[98:99]
	global_load_lds_dwordx4 v[232:233], off
	ds_read_b128 v[170:173], v165
	ds_read_b128 v[174:177], v165 offset:32
	ds_read_b128 v[204:207], v165 offset:8704
	ds_read_b128 v[208:211], v165 offset:8736
	s_waitcnt lgkmcnt(3)
	v_mfma_f32_32x32x16_bf16 v[66:81], v[170:173], v[186:189], v[66:81]
	s_waitcnt lgkmcnt(1)
	v_mfma_f32_32x32x16_bf16 v[34:49], v[204:207], v[186:189], v[34:49]
	v_mfma_f32_32x32x16_bf16 v[66:81], v[174:177], v[190:193], v[66:81]
	ds_read_b128 v[170:173], v0 offset:64
	ds_read_b128 v[174:177], v0 offset:96
	ds_read_b128 v[204:207], v0 offset:8768
	ds_read_b128 v[212:215], v0 offset:8800
	s_waitcnt lgkmcnt(4)
	v_mfma_f32_32x32x16_bf16 v[34:49], v[208:211], v[190:193], v[34:49]
	s_waitcnt lgkmcnt(3)
	v_mfma_f32_32x32x16_bf16 v[66:81], v[170:173], v[150:153], v[66:81]
	s_waitcnt lgkmcnt(1)
	v_mfma_f32_32x32x16_bf16 v[34:49], v[204:207], v[150:153], v[34:49]
	v_mfma_f32_32x32x16_bf16 v[66:81], v[174:177], v[146:149], v[66:81]
	ds_read_b128 v[170:173], v0 offset:128
	ds_read_b128 v[174:177], v0 offset:160
	ds_read_b128 v[204:207], v0 offset:8832
	ds_read_b128 v[208:211], v0 offset:8864
	s_waitcnt lgkmcnt(4)
	v_mfma_f32_32x32x16_bf16 v[34:49], v[212:215], v[146:149], v[34:49]
	s_waitcnt lgkmcnt(3)
	v_mfma_f32_32x32x16_bf16 v[66:81], v[170:173], v[142:145], v[66:81]
	s_waitcnt lgkmcnt(1)
	v_mfma_f32_32x32x16_bf16 v[34:49], v[204:207], v[142:145], v[34:49]
	v_mfma_f32_32x32x16_bf16 v[66:81], v[174:177], v[138:141], v[66:81]
	ds_read_b128 v[170:173], v0 offset:192
	ds_read_b128 v[174:177], v0 offset:224
	ds_read_b128 v[204:207], v0 offset:8896
	ds_read_b128 v[212:215], v0 offset:8928
	s_waitcnt lgkmcnt(4)
	v_mfma_f32_32x32x16_bf16 v[34:49], v[208:211], v[138:141], v[34:49]
	s_waitcnt lgkmcnt(3)
	v_mfma_f32_32x32x16_bf16 v[66:81], v[170:173], v[134:137], v[66:81]
	s_waitcnt lgkmcnt(1)
	v_mfma_f32_32x32x16_bf16 v[34:49], v[204:207], v[134:137], v[34:49]
	v_mfma_f32_32x32x16_bf16 v[66:81], v[174:177], v[130:133], v[66:81]
	s_waitcnt lgkmcnt(0)
	v_mfma_f32_32x32x16_bf16 v[34:49], v[212:215], v[130:133], v[34:49]
	s_waitcnt vmcnt(3)
	s_waitcnt lgkmcnt(0)
	s_barrier
	s_mov_b32 s98, 0x80
	s_mov_b32 s99, 0
	s_lshl_b32 s100, s83, 4
	s_add_i32 m0, s100, 0x0
	v_lshl_add_u64 v[232:233], v[222:223], 0, s[98:99]
	global_load_lds_dwordx4 v[232:233], off
	s_add_i32 m0, s100, 0x2000
	v_lshl_add_u64 v[232:233], v[224:225], 0, s[98:99]
	global_load_lds_dwordx4 v[232:233], off
	s_cmp_lt_u32 s83, 128
	s_mov_b32 s101, 0xd800
	s_cselect_b32 s101, 0x4000, s101
	s_add_i32 m0, s100, s101
	v_lshl_add_u64 v[232:233], v[226:227], 0, s[98:99]
	global_load_lds_dwordx4 v[232:233], off
	ds_read_b128 v[154:157], v165 offset:18432
	ds_read_b128 v[166:169], v165 offset:18464
	ds_read_b128 v[170:173], v165 offset:27136
	ds_read_b128 v[174:177], v165 offset:27168
	s_waitcnt lgkmcnt(3)
	v_mfma_f32_32x32x16_bf16 v[18:33], v[154:157], v[186:189], v[18:33]
	s_waitcnt lgkmcnt(1)
	v_mfma_f32_32x32x16_bf16 v[2:17], v[170:173], v[186:189], v[2:17]
	v_mfma_f32_32x32x16_bf16 v[18:33], v[166:169], v[190:193], v[18:33]
	ds_read_b128 v[154:157], v0 offset:18496
	ds_read_b128 v[164:167], v0 offset:18528
	ds_read_b128 v[168:171], v0 offset:27200
	ds_read_b128 v[186:189], v0 offset:27232
	s_waitcnt lgkmcnt(4)
	v_mfma_f32_32x32x16_bf16 v[2:17], v[174:177], v[190:193], v[2:17]
	s_waitcnt lgkmcnt(3)
	v_mfma_f32_32x32x16_bf16 v[18:33], v[154:157], v[150:153], v[18:33]
	s_waitcnt lgkmcnt(1)
	v_mfma_f32_32x32x16_bf16 v[2:17], v[168:171], v[150:153], v[2:17]
	v_mfma_f32_32x32x16_bf16 v[18:33], v[164:167], v[146:149], v[18:33]
	ds_read_b128 v[150:153], v0 offset:18560
	ds_read_b128 v[154:157], v0 offset:18592
	ds_read_b128 v[164:167], v0 offset:27264
	ds_read_b128 v[168:171], v0 offset:27296
	s_waitcnt lgkmcnt(4)
	v_mfma_f32_32x32x16_bf16 v[2:17], v[186:189], v[146:149], v[2:17]
	s_waitcnt lgkmcnt(3)
	v_mfma_f32_32x32x16_bf16 v[18:33], v[150:153], v[142:145], v[18:33]
	s_waitcnt lgkmcnt(1)
	v_mfma_f32_32x32x16_bf16 v[2:17], v[164:167], v[142:145], v[2:17]
	v_mfma_f32_32x32x16_bf16 v[18:33], v[154:157], v[138:141], v[18:33]
	ds_read_b128 v[142:145], v0 offset:18624
	ds_read_b128 v[146:149], v0 offset:18656
	ds_read_b128 v[150:153], v0 offset:27328
	ds_read_b128 v[154:157], v0 offset:27360
	s_waitcnt lgkmcnt(4)
	v_mfma_f32_32x32x16_bf16 v[2:17], v[168:171], v[138:141], v[2:17]
	s_waitcnt lgkmcnt(3)
	v_mfma_f32_32x32x16_bf16 v[18:33], v[142:145], v[134:137], v[18:33]
	s_waitcnt lgkmcnt(1)
	v_mfma_f32_32x32x16_bf16 v[2:17], v[150:153], v[134:137], v[2:17]
	v_mfma_f32_32x32x16_bf16 v[18:33], v[146:149], v[130:133], v[18:33]
	s_waitcnt lgkmcnt(0)
	v_mfma_f32_32x32x16_bf16 v[2:17], v[154:157], v[130:133], v[2:17]
	v_max3_f32 v0, v114, s33, v115
	v_max3_f32 v0, v0, v116, v117
	v_max3_f32 v0, v0, v118, v119
	v_max3_f32 v0, v0, v120, v121
	v_max3_f32 v0, v0, v122, v123
	v_max3_f32 v0, v0, v124, v125
	v_max3_f32 v0, v0, v126, v127
	v_max3_f32 v0, v0, v128, v129
	v_max3_f32 v0, v0, v82, v83
	v_max3_f32 v0, v0, v84, v85
	v_max3_f32 v0, v0, v86, v87
	v_max3_f32 v0, v0, v88, v89
	v_max3_f32 v0, v0, v90, v91
	v_max3_f32 v0, v0, v92, v93
	v_max3_f32 v0, v0, v94, v95
	v_max3_f32 v0, v0, v96, v97
	v_max3_f32 v0, v0, v98, v99
	v_max3_f32 v0, v0, v100, v101
	v_max3_f32 v0, v0, v102, v103
	v_max3_f32 v0, v0, v104, v105
	v_max3_f32 v0, v0, v106, v107
	v_max3_f32 v0, v0, v108, v109
	v_max3_f32 v0, v0, v110, v111
	v_max3_f32 v0, v0, v112, v113
	v_max3_f32 v0, v0, v50, v51
	v_max3_f32 v0, v0, v52, v53
	v_max3_f32 v0, v0, v54, v55
	v_max3_f32 v0, v0, v56, v57
	v_max3_f32 v0, v0, v58, v59
	v_max3_f32 v0, v0, v60, v61
	v_max3_f32 v0, v0, v62, v63
	v_max3_f32 v0, v0, v64, v65
	v_max3_f32 v0, v0, v66, v67
	v_max3_f32 v0, v0, v68, v69
	v_max3_f32 v0, v0, v70, v71
	v_max3_f32 v0, v0, v72, v73
	v_max3_f32 v0, v0, v74, v75
	v_max3_f32 v0, v0, v76, v77
	v_max3_f32 v0, v0, v78, v79
	v_max3_f32 v0, v0, v80, v81
	v_max3_f32 v0, v0, v34, v35
	v_max3_f32 v0, v0, v36, v37
	v_max3_f32 v0, v0, v38, v39
	v_max3_f32 v0, v0, v40, v41
	v_max3_f32 v0, v0, v42, v43
	v_max3_f32 v0, v0, v44, v45
	v_max3_f32 v0, v0, v46, v47
	v_max3_f32 v0, v0, v48, v49
	v_max3_f32 v0, v0, v18, v19
	v_max3_f32 v0, v0, v20, v21
	v_max3_f32 v0, v0, v22, v23
	v_max3_f32 v0, v0, v24, v25
	v_max3_f32 v0, v0, v26, v27
	v_max3_f32 v0, v0, v28, v29
	v_max3_f32 v0, v0, v30, v31
	v_max3_f32 v0, v0, v32, v33
	v_max3_f32 v0, v0, v2, v3
	v_max3_f32 v0, v0, v4, v5
	v_max3_f32 v0, v0, v6, v7
	v_max3_f32 v0, v0, v8, v9
	v_max3_f32 v0, v0, v10, v11
	v_max3_f32 v0, v0, v12, v13
	v_max3_f32 v0, v0, v14, v15
	v_max3_f32 v0, v0, v16, v17
	v_mov_b32_e32 v130, v0
	v_mov_b32_e32 v131, v0
	s_nop 1
	v_permlane32_swap_b32_e32 v130, v131
	v_cmp_eq_u32_e32 vcc, v130, v0
	s_lshl_b32 s1, s1, 9
	v_readlane_b32 s4, v255, 43
	v_cndmask_b32_e32 v130, v130, v131, vcc
	v_max_f32_e32 v130, v130, v130
	v_max_f32_e32 v131, v0, v130
	v_mov_b32_e32 v130, v17
	v_pk_mul_f32 v[130:131], v[130:131], s[76:77] op_sel_hi:[1,0]
	v_ashrrev_i32_e32 v166, 3, v182
	v_fma_f32 v0, v114, s76, -v131
	v_exp_f32_e32 v0, v0
	v_fma_f32 v17, v115, s76, -v131
	v_exp_f32_e32 v17, v17
	v_fma_f32 v114, v116, s76, -v131
	v_exp_f32_e32 v115, v114
	v_fma_f32 v114, v117, s76, -v131
	v_exp_f32_e32 v116, v114
	v_fma_f32 v117, v118, s76, -v131
	v_add_f32_e32 v114, 0, v0
	v_exp_f32_e32 v117, v117
	v_fma_f32 v118, v119, s76, -v131
	v_add_f32_e32 v114, v17, v114
	v_exp_f32_e32 v118, v118
	v_fma_f32 v119, v120, s76, -v131
	v_add_f32_e32 v114, v115, v114
	v_exp_f32_e32 v119, v119
	v_fma_f32 v120, v121, s76, -v131
	v_add_f32_e32 v114, v116, v114
	v_exp_f32_e32 v120, v120
	v_add_f32_e32 v114, v117, v114
	v_add_f32_e32 v114, v118, v114
	v_add_f32_e32 v114, v119, v114
	v_add_f32_e32 v121, v120, v114
	v_cvt_pk_bf16_f32 v114, v0, v17
	v_fma_f32 v0, v122, s76, -v131
	v_exp_f32_e32 v0, v0
	v_fma_f32 v17, v123, s76, -v131
	v_cvt_pk_bf16_f32 v115, v115, v116
	v_cvt_pk_bf16_f32 v116, v117, v118
	v_exp_f32_e32 v17, v17
	v_fma_f32 v118, v124, s76, -v131
	v_cvt_pk_bf16_f32 v117, v119, v120
	v_exp_f32_e32 v119, v118
	v_fma_f32 v118, v125, s76, -v131
	v_exp_f32_e32 v120, v118
	v_add_f32_e32 v118, v0, v121
	v_fma_f32 v121, v126, s76, -v131
	v_exp_f32_e32 v121, v121
	v_fma_f32 v122, v127, s76, -v131
	v_add_f32_e32 v118, v17, v118
	v_exp_f32_e32 v122, v122
	v_fma_f32 v123, v128, s76, -v131
	v_add_f32_e32 v118, v119, v118
	v_exp_f32_e32 v123, v123
	v_fma_f32 v124, v129, s76, -v131
	v_add_f32_e32 v118, v120, v118
	v_exp_f32_e32 v124, v124
	v_add_f32_e32 v118, v121, v118
	v_add_f32_e32 v118, v122, v118
	v_add_f32_e32 v118, v123, v118
	v_add_f32_e32 v125, v124, v118
	v_cvt_pk_bf16_f32 v118, v0, v17
	v_fma_f32 v0, v82, s76, -v131
	v_exp_f32_e32 v0, v0
	v_fma_f32 v17, v83, s76, -v131
	v_exp_f32_e32 v17, v17
	v_fma_f32 v82, v84, s76, -v131
	v_exp_f32_e32 v83, v82
	v_fma_f32 v82, v85, s76, -v131
	v_exp_f32_e32 v84, v82
	v_fma_f32 v85, v86, s76, -v131
	v_add_f32_e32 v82, v0, v125
	v_exp_f32_e32 v85, v85
	v_fma_f32 v86, v87, s76, -v131
	v_add_f32_e32 v82, v17, v82
	v_exp_f32_e32 v86, v86
	v_fma_f32 v87, v88, s76, -v131
	v_add_f32_e32 v82, v83, v82
	v_exp_f32_e32 v87, v87
	v_fma_f32 v88, v89, s76, -v131
	v_add_f32_e32 v82, v84, v82
	v_exp_f32_e32 v88, v88
	v_add_f32_e32 v82, v85, v82
	v_add_f32_e32 v82, v86, v82
	v_add_f32_e32 v82, v87, v82
	v_add_f32_e32 v89, v88, v82
	v_cvt_pk_bf16_f32 v82, v0, v17
	v_fma_f32 v0, v90, s76, -v131
	v_exp_f32_e32 v0, v0
	v_fma_f32 v17, v91, s76, -v131
	v_cvt_pk_bf16_f32 v83, v83, v84
	v_cvt_pk_bf16_f32 v84, v85, v86
	v_exp_f32_e32 v17, v17
	v_fma_f32 v86, v92, s76, -v131
	v_cvt_pk_bf16_f32 v85, v87, v88
	v_exp_f32_e32 v87, v86
	v_fma_f32 v86, v93, s76, -v131
	v_exp_f32_e32 v88, v86
	v_add_f32_e32 v86, v0, v89
	v_fma_f32 v89, v94, s76, -v131
	v_exp_f32_e32 v89, v89
	v_fma_f32 v90, v95, s76, -v131
	v_add_f32_e32 v86, v17, v86
	v_exp_f32_e32 v90, v90
	v_fma_f32 v91, v96, s76, -v131
	v_add_f32_e32 v86, v87, v86
	v_exp_f32_e32 v91, v91
	v_fma_f32 v92, v97, s76, -v131
	v_add_f32_e32 v86, v88, v86
	v_exp_f32_e32 v92, v92
	v_add_f32_e32 v86, v89, v86
	v_add_f32_e32 v86, v90, v86
	v_add_f32_e32 v86, v91, v86
	v_add_f32_e32 v93, v92, v86
	v_cvt_pk_bf16_f32 v86, v0, v17
	v_fma_f32 v0, v98, s76, -v131
	v_exp_f32_e32 v0, v0
	v_fma_f32 v17, v99, s76, -v131
	v_cvt_pk_bf16_f32 v87, v87, v88
	v_cvt_pk_bf16_f32 v88, v89, v90
	v_exp_f32_e32 v17, v17
	v_fma_f32 v90, v100, s76, -v131
	v_cvt_pk_bf16_f32 v89, v91, v92
	v_exp_f32_e32 v91, v90
	v_fma_f32 v90, v101, s76, -v131
	v_exp_f32_e32 v92, v90
	v_add_f32_e32 v90, v0, v93
	v_fma_f32 v93, v102, s76, -v131
	v_exp_f32_e32 v93, v93
	v_fma_f32 v94, v103, s76, -v131
	v_add_f32_e32 v90, v17, v90
	v_exp_f32_e32 v94, v94
	v_fma_f32 v95, v104, s76, -v131
	v_add_f32_e32 v90, v91, v90
	v_exp_f32_e32 v95, v95
	v_fma_f32 v96, v105, s76, -v131
	v_add_f32_e32 v90, v92, v90
	v_exp_f32_e32 v96, v96
	v_add_f32_e32 v90, v93, v90
	v_add_f32_e32 v90, v94, v90
	v_add_f32_e32 v90, v95, v90
	v_add_f32_e32 v97, v96, v90
	v_cvt_pk_bf16_f32 v90, v0, v17
	v_fma_f32 v0, v106, s76, -v131
	v_exp_f32_e32 v0, v0
	v_fma_f32 v17, v107, s76, -v131
	v_cvt_pk_bf16_f32 v91, v91, v92
	v_cvt_pk_bf16_f32 v92, v93, v94
	v_exp_f32_e32 v17, v17
	v_fma_f32 v94, v108, s76, -v131
	v_cvt_pk_bf16_f32 v93, v95, v96
	v_exp_f32_e32 v95, v94
	v_fma_f32 v94, v109, s76, -v131
	v_exp_f32_e32 v96, v94
	v_add_f32_e32 v94, v0, v97
	v_fma_f32 v97, v110, s76, -v131
	v_exp_f32_e32 v97, v97
	v_fma_f32 v98, v111, s76, -v131
	v_add_f32_e32 v94, v17, v94
	v_exp_f32_e32 v98, v98
	v_fma_f32 v99, v112, s76, -v131
	v_add_f32_e32 v94, v95, v94
	v_exp_f32_e32 v99, v99
	v_fma_f32 v100, v113, s76, -v131
	v_add_f32_e32 v94, v96, v94
	v_exp_f32_e32 v100, v100
	v_add_f32_e32 v94, v97, v94
	v_add_f32_e32 v94, v98, v94
	v_add_f32_e32 v94, v99, v94
	v_add_f32_e32 v101, v100, v94
	v_cvt_pk_bf16_f32 v94, v0, v17
	v_fma_f32 v0, v50, s76, -v131
	v_exp_f32_e32 v0, v0
	v_fma_f32 v17, v51, s76, -v131
	v_exp_f32_e32 v17, v17
	v_fma_f32 v50, v52, s76, -v131
	v_exp_f32_e32 v50, v50
	v_fma_f32 v51, v53, s76, -v131
	v_exp_f32_e32 v51, v51
	v_fma_f32 v53, v54, s76, -v131
	v_add_f32_e32 v52, v0, v101
	v_exp_f32_e32 v53, v53
	v_fma_f32 v54, v55, s76, -v131
	v_add_f32_e32 v52, v17, v52
	v_exp_f32_e32 v54, v54
	v_fma_f32 v55, v56, s76, -v131
	v_add_f32_e32 v52, v50, v52
	v_exp_f32_e32 v55, v55
	v_fma_f32 v56, v57, s76, -v131
	v_cvt_pk_bf16_f32 v95, v95, v96
	v_cvt_pk_bf16_f32 v96, v97, v98
	v_add_f32_e32 v52, v51, v52
	v_exp_f32_e32 v56, v56
	v_cvt_pk_bf16_f32 v98, v0, v17
	v_fma_f32 v0, v58, s76, -v131
	v_add_f32_e32 v52, v53, v52
	v_exp_f32_e32 v0, v0
	v_fma_f32 v17, v59, s76, -v131
	v_cvt_pk_bf16_f32 v97, v99, v100
	v_add_f32_e32 v52, v54, v52
	v_cvt_pk_bf16_f32 v99, v50, v51
	v_exp_f32_e32 v17, v17
	v_fma_f32 v50, v60, s76, -v131
	v_add_f32_e32 v52, v55, v52
	v_exp_f32_e32 v50, v50
	v_fma_f32 v51, v61, s76, -v131
	v_add_f32_e32 v52, v56, v52
	v_cvt_pk_bf16_f32 v100, v53, v54
	v_exp_f32_e32 v51, v51
	v_fma_f32 v53, v62, s76, -v131
	v_add_f32_e32 v52, v0, v52
	v_exp_f32_e32 v53, v53
	v_fma_f32 v54, v63, s76, -v131
	v_cvt_pk_bf16_f32 v101, v55, v56
	v_add_f32_e32 v52, v17, v52
	v_exp_f32_e32 v54, v54
	v_fma_f32 v55, v64, s76, -v131
	v_add_f32_e32 v52, v50, v52
	v_exp_f32_e32 v55, v55
	v_fma_f32 v56, v65, s76, -v131
	v_add_f32_e32 v52, v51, v52
	v_exp_f32_e32 v56, v56
	v_cvt_pk_bf16_f32 v102, v0, v17
	v_fma_f32 v0, v66, s76, -v131
	v_add_f32_e32 v52, v53, v52
	v_exp_f32_e32 v0, v0
	v_fma_f32 v17, v67, s76, -v131
	v_add_f32_e32 v52, v54, v52
	v_cvt_pk_bf16_f32 v103, v50, v51
	v_exp_f32_e32 v17, v17
	v_fma_f32 v50, v68, s76, -v131
	v_add_f32_e32 v52, v55, v52
	v_exp_f32_e32 v50, v50
	v_fma_f32 v51, v69, s76, -v131
	v_add_f32_e32 v52, v56, v52
	v_cvt_pk_bf16_f32 v104, v53, v54
	v_exp_f32_e32 v51, v51
	v_fma_f32 v53, v70, s76, -v131
	v_add_f32_e32 v52, v0, v52
	v_exp_f32_e32 v53, v53
	v_fma_f32 v54, v71, s76, -v131
	v_cvt_pk_bf16_f32 v105, v55, v56
	v_add_f32_e32 v52, v17, v52
	v_exp_f32_e32 v54, v54
	v_fma_f32 v55, v72, s76, -v131
	v_add_f32_e32 v52, v50, v52
	v_exp_f32_e32 v55, v55
	v_fma_f32 v56, v73, s76, -v131
	v_add_f32_e32 v52, v51, v52
	v_exp_f32_e32 v56, v56
	v_cvt_pk_bf16_f32 v66, v0, v17
	v_fma_f32 v0, v74, s76, -v131
	v_add_f32_e32 v52, v53, v52
	v_exp_f32_e32 v0, v0
	v_fma_f32 v17, v75, s76, -v131
	v_add_f32_e32 v52, v54, v52
	v_cvt_pk_bf16_f32 v67, v50, v51
	v_exp_f32_e32 v17, v17
	v_fma_f32 v50, v76, s76, -v131
	v_add_f32_e32 v52, v55, v52
	v_exp_f32_e32 v50, v50
	v_fma_f32 v51, v77, s76, -v131
	v_add_f32_e32 v52, v56, v52
	v_cvt_pk_bf16_f32 v68, v53, v54
	v_exp_f32_e32 v51, v51
	v_fma_f32 v53, v78, s76, -v131
	v_add_f32_e32 v52, v0, v52
	v_exp_f32_e32 v53, v53
	v_fma_f32 v54, v79, s76, -v131
	v_cvt_pk_bf16_f32 v69, v55, v56
	v_add_f32_e32 v52, v17, v52
	v_exp_f32_e32 v54, v54
	v_fma_f32 v55, v80, s76, -v131
	v_add_f32_e32 v52, v50, v52
	v_exp_f32_e32 v55, v55
	v_fma_f32 v56, v81, s76, -v131
	v_add_f32_e32 v52, v51, v52
	v_exp_f32_e32 v56, v56
	v_cvt_pk_bf16_f32 v70, v0, v17
	v_fma_f32 v0, v34, s76, -v131
	v_add_f32_e32 v52, v53, v52
	v_exp_f32_e32 v0, v0
	v_fma_f32 v17, v35, s76, -v131
	v_add_f32_e32 v52, v54, v52
	v_exp_f32_e32 v17, v17
	v_fma_f32 v34, v36, s76, -v131
	v_add_f32_e32 v52, v55, v52
	v_exp_f32_e32 v34, v34
	v_fma_f32 v35, v37, s76, -v131
	v_add_f32_e32 v52, v56, v52
	v_exp_f32_e32 v35, v35
	v_fma_f32 v37, v38, s76, -v131
	v_add_f32_e32 v36, v0, v52
	v_exp_f32_e32 v37, v37
	v_fma_f32 v38, v39, s76, -v131
	v_add_f32_e32 v36, v17, v36
	v_exp_f32_e32 v38, v38
	v_fma_f32 v39, v40, s76, -v131
	v_add_f32_e32 v36, v34, v36
	v_exp_f32_e32 v39, v39
	v_fma_f32 v40, v41, s76, -v131
	v_add_f32_e32 v36, v35, v36
	v_exp_f32_e32 v40, v40
	v_cvt_pk_bf16_f32 v74, v0, v17
	v_fma_f32 v0, v42, s76, -v131
	v_add_f32_e32 v36, v37, v36
	v_exp_f32_e32 v17, v0
	v_cvt_pk_bf16_f32 v75, v34, v35
	v_fma_f32 v34, v43, s76, -v131
	v_add_f32_e32 v36, v38, v36
	v_exp_f32_e32 v42, v34
	v_fma_f32 v34, v44, s76, -v131
	v_add_f32_e32 v36, v39, v36
	v_exp_f32_e32 v43, v34
	v_fma_f32 v34, v45, s76, -v131
	v_add_f32_e32 v36, v40, v36
	v_exp_f32_e32 v44, v34
	v_fma_f32 v34, v46, s76, -v131
	v_add_f32_e32 v0, v17, v36
	v_exp_f32_e32 v45, v34
	v_add_f32_e32 v0, v42, v0
	v_add_f32_e32 v0, v43, v0
	v_add_f32_e32 v0, v44, v0
	v_add_f32_e32 v46, v45, v0
	v_fma_f32 v0, v47, s76, -v131
	v_exp_f32_e32 v47, v0
	v_fma_f32 v0, v48, s76, -v131
	v_ashrrev_i32_e32 v167, 3, v184
	v_cvt_pk_bf16_f32 v76, v37, v38
	v_exp_f32_e32 v48, v0
	v_fma_f32 v0, v49, s76, -v131
	s_add_u32 s4, s4, s1
	v_readlane_b32 s1, v255, 44
	v_add_u32_e32 v34, s0, v166
	v_add_u32_e32 v38, s0, v167
	v_cvt_pk_bf16_f32 v77, v39, v40
	v_exp_f32_e32 v49, v0
	s_addc_u32 s5, s1, 0
	v_and_b32_e32 v0, 0x70, v183
	v_ashrrev_i32_e32 v35, 31, v34
	v_ashrrev_i32_e32 v39, 31, v38
	v_lshl_add_u64 v[140:141], s[4:5], 0, v[0:1]
	v_lshlrev_b64 v[34:35], 11, v[34:35]
	v_lshlrev_b64 v[38:39], 11, v[38:39]
	v_lshl_add_u64 v[138:139], v[140:141], 0, v[34:35]
	v_lshl_add_u64 v[142:143], v[140:141], 0, v[38:39]
	s_barrier
	v_add_u32_e32 v0, 0, v0
	v_mad_u64_u32 v[132:133], s[4:5], v166, s86, v[0:1]
	v_mad_u64_u32 v[134:135], s[4:5], v167, s86, v[0:1]
	v_cvt_pk_bf16_f32 v78, v17, v42
	v_fma_f32 v17, v18, s76, -v131
	v_exp_f32_e32 v17, v17
	v_fma_f32 v18, v19, s76, -v131
	v_add_f32_e32 v46, v47, v46
	v_exp_f32_e32 v18, v18
	v_fma_f32 v19, v20, s76, -v131
	v_add_f32_e32 v46, v48, v46
	v_exp_f32_e32 v19, v19
	v_fma_f32 v20, v21, s76, -v131
	v_add_f32_e32 v46, v49, v46
	v_exp_f32_e32 v20, v20
	v_fma_f32 v22, v22, s76, -v131
	v_add_f32_e32 v21, v17, v46
	v_exp_f32_e32 v22, v22
	v_fma_f32 v23, v23, s76, -v131
	v_add_f32_e32 v21, v18, v21
	v_exp_f32_e32 v23, v23
	v_fma_f32 v24, v24, s76, -v131
	v_add_f32_e32 v21, v19, v21
	v_exp_f32_e32 v24, v24
	v_fma_f32 v25, v25, s76, -v131
	v_add_f32_e32 v21, v20, v21
	v_exp_f32_e32 v25, v25
	v_cvt_pk_bf16_f32 v106, v17, v18
	v_fma_f32 v17, v26, s76, -v131
	v_add_f32_e32 v21, v22, v21
	v_exp_f32_e32 v17, v17
	v_fma_f32 v18, v27, s76, -v131
	v_add_f32_e32 v21, v23, v21
	v_cvt_pk_bf16_f32 v107, v19, v20
	v_exp_f32_e32 v18, v18
	v_fma_f32 v19, v28, s76, -v131
	v_add_f32_e32 v21, v24, v21
	v_exp_f32_e32 v19, v19
	v_fma_f32 v20, v29, s76, -v131
	v_add_f32_e32 v21, v25, v21
	v_cvt_pk_bf16_f32 v108, v22, v23
	v_exp_f32_e32 v20, v20
	v_fma_f32 v22, v30, s76, -v131
	v_add_f32_e32 v21, v17, v21
	v_exp_f32_e32 v22, v22
	v_fma_f32 v23, v31, s76, -v131
	v_cvt_pk_bf16_f32 v109, v24, v25
	v_add_f32_e32 v21, v18, v21
	v_exp_f32_e32 v23, v23
	v_fma_f32 v24, v32, s76, -v131
	v_add_f32_e32 v21, v19, v21
	v_exp_f32_e32 v24, v24
	v_fma_f32 v25, v33, s76, -v131
	v_add_f32_e32 v21, v20, v21
	v_exp_f32_e32 v25, v25
	v_fma_f32 v2, v2, s76, -v131
	v_add_f32_e32 v21, v22, v21
	v_exp_f32_e32 v2, v2
	v_fma_f32 v3, v3, s76, -v131
	v_add_f32_e32 v21, v23, v21
	v_exp_f32_e32 v3, v3
	v_fma_f32 v4, v4, s76, -v131
	v_add_f32_e32 v21, v24, v21
	v_exp_f32_e32 v4, v4
	v_fma_f32 v5, v5, s76, -v131
	v_add_f32_e32 v21, v25, v21
	v_exp_f32_e32 v5, v5
	v_fma_f32 v6, v6, s76, -v131
	v_cvt_pk_bf16_f32 v110, v17, v18
	v_add_f32_e32 v17, v2, v21
	v_exp_f32_e32 v6, v6
	v_fma_f32 v7, v7, s76, -v131
	v_add_f32_e32 v17, v3, v17
	v_exp_f32_e32 v7, v7
	v_fma_f32 v8, v8, s76, -v131
	v_add_f32_e32 v0, v4, v17
	s_waitcnt vmcnt(3)
	s_waitcnt lgkmcnt(0)
	s_barrier
	s_mov_b32 s98, 0x100
	s_mov_b32 s99, 0
	s_lshl_b32 s100, s83, 4
	s_add_i32 m0, s100, 0x4800
	v_lshl_add_u64 v[232:233], v[222:223], 0, s[98:99]
	global_load_lds_dwordx4 v[232:233], off
	s_add_i32 m0, s100, 0x6800
	v_lshl_add_u64 v[232:233], v[224:225], 0, s[98:99]
	global_load_lds_dwordx4 v[232:233], off
	s_cmp_lt_u32 s83, 128
	s_mov_b32 s101, 0xd800
	s_cselect_b32 s101, 0x8800, s101
	s_add_i32 m0, s100, s101
	v_lshl_add_u64 v[232:233], v[226:227], 0, s[98:99]
	global_load_lds_dwordx4 v[232:233], off
	v_exp_f32_e32 v8, v8
	v_fma_f32 v9, v9, s76, -v131
	v_cvt_pk_bf16_f32 v119, v119, v120
	v_cvt_pk_bf16_f32 v120, v121, v122
	v_add_f32_e32 v0, v5, v0
	v_exp_f32_e32 v9, v9
	v_cvt_pk_bf16_f32 v122, v2, v3
	v_fma_f32 v2, v10, s76, -v131
	v_add_f32_e32 v0, v6, v0
	v_exp_f32_e32 v2, v2
	v_fma_f32 v3, v11, s76, -v131
	v_cvt_pk_bf16_f32 v121, v123, v124
	v_add_f32_e32 v0, v7, v0
	v_cvt_pk_bf16_f32 v123, v4, v5
	v_exp_f32_e32 v3, v3
	v_fma_f32 v4, v12, s76, -v131
	v_add_f32_e32 v0, v8, v0
	v_exp_f32_e32 v4, v4
	v_fma_f32 v5, v13, s76, -v131
	v_add_f32_e32 v0, v9, v0
	v_cvt_pk_bf16_f32 v124, v6, v7
	v_exp_f32_e32 v5, v5
	v_fma_f32 v6, v14, s76, -v131
	v_add_f32_e32 v0, v2, v0
	v_exp_f32_e32 v6, v6
	v_fma_f32 v7, v15, s76, -v131
	v_cvt_pk_bf16_f32 v125, v8, v9
	v_add_f32_e32 v0, v3, v0
	v_exp_f32_e32 v7, v7
	v_fma_f32 v8, v16, s76, -v131
	v_add_f32_e32 v0, v4, v0
	v_exp_f32_e32 v8, v8
	v_sub_f32_e32 v9, v130, v131
	v_add_f32_e32 v0, v5, v0
	v_exp_f32_e32 v9, v9
	v_add_f32_e32 v0, v6, v0
	v_add_f32_e32 v0, v7, v0
	v_add_f32_e32 v0, v8, v0
	v_add_f32_e32 v0, v9, v0
	v_cvt_pk_bf16_f32 v126, v2, v3
	v_mov_b32_e32 v2, v0
	v_mov_b32_e32 v3, v0
	s_nop 1
	v_permlane32_swap_b32_e32 v2, v3
	v_cmp_eq_u32_e32 vcc, v2, v0
	v_cvt_pk_bf16_f32 v127, v4, v5
	v_cvt_pk_bf16_f32 v128, v6, v7
	v_cndmask_b32_e32 v2, v2, v3, vcc
	v_add_f32_e32 v0, v0, v2
	v_div_scale_f32 v2, s[4:5], v0, v0, 1.0
	v_rcp_f32_e32 v3, v2
	v_mad_u32_u24 v133, v180, s86, v163
	v_cvt_pk_bf16_f32 v129, v8, v9
	v_lshlrev_b32_e32 v18, 2, v181
	v_fma_f32 v4, -v2, v3, 1.0
	v_fmac_f32_e32 v3, v4, v3
	v_div_scale_f32 v4, vcc, 1.0, v0, 1.0
	v_mul_f32_e32 v5, v4, v3
	v_fma_f32 v6, -v2, v5, v4
	v_fmac_f32_e32 v5, v6, v3
	v_fma_f32 v2, -v2, v5, v4
	v_div_fmas_f32 v2, v2, v3, v5
	v_div_fixup_f32 v0, v2, v0, 1.0
	ds_read_b128 v[2:5], v133 offset:36864
	ds_read_b128 v[6:9], v133 offset:41472
	ds_read_b128 v[10:13], v133 offset:46080
	ds_read_b128 v[14:17], v133 offset:50688
	v_cvt_pk_bf16_f32 v111, v19, v20
	v_ashrrev_i32_e32 v19, 31, v18
	v_lshl_add_u64 v[144:145], v[18:19], 1, v[160:161]
	s_mov_b64 s[4:5], 0x4800
	v_lshl_add_u64 v[136:137], v[144:145], 0, s[4:5]
	v_readlane_b32 s4, v255, 45
	v_add_u32_e32 v130, s0, v18
	v_lshlrev_b64 v[18:19], 11, v[158:159]
	v_readlane_b32 s5, v255, 46
	v_cvt_pk_bf16_f32 v71, v50, v51
	v_cvt_pk_bf16_f32 v72, v53, v54
	v_cvt_pk_bf16_f32 v73, v55, v56
	v_cvt_pk_bf16_f32 v79, v43, v44
	v_cvt_pk_bf16_f32 v80, v45, v47
	v_cvt_pk_bf16_f32 v81, v48, v49
	v_cvt_pk_bf16_f32 v112, v22, v23
	v_cvt_pk_bf16_f32 v113, v24, v25
	v_lshl_add_u64 v[168:169], s[4:5], 0, v[18:19]
	ds_read_b128 v[154:157], v133 offset:36896
	ds_read_b128 v[158:161], v133 offset:41504
	ds_read_b128 v[162:165], v133 offset:46112
	ds_read_b128 v[170:173], v133 offset:50720
	s_waitcnt lgkmcnt(7)
	v_mfma_f32_32x32x16_bf16 v[50:65], v[2:5], v[114:117], 0
	s_waitcnt lgkmcnt(6)
	v_mfma_f32_32x32x16_bf16 v[34:49], v[6:9], v[114:117], 0
	s_waitcnt lgkmcnt(5)
	v_mfma_f32_32x32x16_bf16 v[18:33], v[10:13], v[114:117], 0
	s_waitcnt lgkmcnt(4)
	v_mfma_f32_32x32x16_bf16 v[2:17], v[14:17], v[114:117], 0
	s_waitcnt lgkmcnt(3)
	v_mfma_f32_32x32x16_bf16 v[50:65], v[154:157], v[118:121], v[50:65]
	s_waitcnt lgkmcnt(2)
	v_mfma_f32_32x32x16_bf16 v[34:49], v[158:161], v[118:121], v[34:49]
	s_waitcnt lgkmcnt(1)
	v_mfma_f32_32x32x16_bf16 v[18:33], v[162:165], v[118:121], v[18:33]
	ds_read_b128 v[154:157], v133 offset:36928
	ds_read_b128 v[158:161], v133 offset:41536
	ds_read_b128 v[162:165], v133 offset:46144
	ds_read_b128 v[174:177], v133 offset:50752
	s_waitcnt lgkmcnt(4)
	v_mfma_f32_32x32x16_bf16 v[2:17], v[170:173], v[118:121], v[2:17]
	s_waitcnt lgkmcnt(3)
	v_mfma_f32_32x32x16_bf16 v[50:65], v[154:157], v[82:85], v[50:65]
	s_waitcnt lgkmcnt(2)
	v_mfma_f32_32x32x16_bf16 v[34:49], v[158:161], v[82:85], v[34:49]
	s_waitcnt lgkmcnt(1)
	v_mfma_f32_32x32x16_bf16 v[18:33], v[162:165], v[82:85], v[18:33]
	ds_read_b128 v[154:157], v133 offset:36960
	ds_read_b128 v[158:161], v133 offset:41568
	ds_read_b128 v[162:165], v133 offset:46176
	ds_read_b128 v[170:173], v133 offset:50784
	s_waitcnt lgkmcnt(4)
	v_mfma_f32_32x32x16_bf16 v[2:17], v[174:177], v[82:85], v[2:17]
	s_waitcnt lgkmcnt(3)
	v_mfma_f32_32x32x16_bf16 v[50:65], v[154:157], v[86:89], v[50:65]
	s_waitcnt lgkmcnt(2)
	v_mfma_f32_32x32x16_bf16 v[34:49], v[158:161], v[86:89], v[34:49]
	s_waitcnt lgkmcnt(1)
	v_mfma_f32_32x32x16_bf16 v[18:33], v[162:165], v[86:89], v[18:33]
	s_waitcnt lgkmcnt(0)
	v_mfma_f32_32x32x16_bf16 v[2:17], v[170:173], v[86:89], v[2:17]
	s_waitcnt vmcnt(3)
	s_waitcnt lgkmcnt(0)
	s_barrier
	s_mov_b32 s98, 0x180
	s_mov_b32 s99, 0
	s_lshl_b32 s100, s83, 4
	s_add_i32 m0, s100, 0x9000
	v_lshl_add_u64 v[232:233], v[222:223], 0, s[98:99]
	global_load_lds_dwordx4 v[232:233], off
	s_add_i32 m0, s100, 0xb000
	v_lshl_add_u64 v[232:233], v[224:225], 0, s[98:99]
	global_load_lds_dwordx4 v[232:233], off
	s_cmp_lt_u32 s83, 128
	s_mov_b32 s101, 0xd800
	s_cselect_b32 s101, 0xd000, s101
	s_add_i32 m0, s100, s101
	v_lshl_add_u64 v[232:233], v[226:227], 0, s[98:99]
	global_load_lds_dwordx4 v[232:233], off
	ds_read_b128 v[154:157], v133
	ds_read_b128 v[158:161], v133 offset:4608
	ds_read_b128 v[162:165], v133 offset:9216
	ds_read_b128 v[170:173], v133 offset:13824
	s_waitcnt lgkmcnt(3)
	v_mfma_f32_32x32x16_bf16 v[50:65], v[154:157], v[90:93], v[50:65]
	s_waitcnt lgkmcnt(2)
	v_mfma_f32_32x32x16_bf16 v[34:49], v[158:161], v[90:93], v[34:49]
	s_waitcnt lgkmcnt(1)
	v_mfma_f32_32x32x16_bf16 v[18:33], v[162:165], v[90:93], v[18:33]
	ds_read_b128 v[154:157], v133 offset:32
	ds_read_b128 v[158:161], v133 offset:4640
	ds_read_b128 v[162:165], v133 offset:9248
	ds_read_b128 v[174:177], v133 offset:13856
	s_waitcnt lgkmcnt(4)
	v_mfma_f32_32x32x16_bf16 v[2:17], v[170:173], v[90:93], v[2:17]
	s_waitcnt lgkmcnt(3)
	v_mfma_f32_32x32x16_bf16 v[50:65], v[154:157], v[94:97], v[50:65]
	s_waitcnt lgkmcnt(2)
	v_mfma_f32_32x32x16_bf16 v[34:49], v[158:161], v[94:97], v[34:49]
	s_waitcnt lgkmcnt(1)
	v_mfma_f32_32x32x16_bf16 v[18:33], v[162:165], v[94:97], v[18:33]
	ds_read_b128 v[154:157], v133 offset:64
	ds_read_b128 v[158:161], v133 offset:4672
	ds_read_b128 v[162:165], v133 offset:9280
	ds_read_b128 v[170:173], v133 offset:13888
	s_waitcnt lgkmcnt(4)
	v_mfma_f32_32x32x16_bf16 v[2:17], v[174:177], v[94:97], v[2:17]
	s_waitcnt lgkmcnt(3)
	v_mfma_f32_32x32x16_bf16 v[50:65], v[154:157], v[98:101], v[50:65]
	s_waitcnt lgkmcnt(2)
	v_mfma_f32_32x32x16_bf16 v[34:49], v[158:161], v[98:101], v[34:49]
	s_waitcnt lgkmcnt(1)
	v_mfma_f32_32x32x16_bf16 v[18:33], v[162:165], v[98:101], v[18:33]
	ds_read_b128 v[154:157], v133 offset:96
	ds_read_b128 v[158:161], v133 offset:4704
	ds_read_b128 v[162:165], v133 offset:9312
	ds_read_b128 v[174:177], v133 offset:13920
	s_waitcnt lgkmcnt(4)
	v_mfma_f32_32x32x16_bf16 v[2:17], v[170:173], v[98:101], v[2:17]
	s_waitcnt lgkmcnt(3)
	v_mfma_f32_32x32x16_bf16 v[50:65], v[154:157], v[102:105], v[50:65]
	s_waitcnt lgkmcnt(2)
	v_mfma_f32_32x32x16_bf16 v[34:49], v[158:161], v[102:105], v[34:49]
	s_waitcnt lgkmcnt(1)
	v_mfma_f32_32x32x16_bf16 v[18:33], v[162:165], v[102:105], v[18:33]
	s_waitcnt lgkmcnt(0)
	v_mfma_f32_32x32x16_bf16 v[2:17], v[174:177], v[102:105], v[2:17]
	s_waitcnt vmcnt(3)
	s_waitcnt lgkmcnt(0)
	s_barrier
	s_mov_b32 s98, 0x40000
	s_mov_b32 s99, 0
	s_lshl_b32 s100, s83, 4
	s_add_i32 m0, s100, 0x0
	v_lshl_add_u64 v[232:233], v[222:223], 0, s[98:99]
	global_load_lds_dwordx4 v[232:233], off
	s_add_i32 m0, s100, 0x2000
	v_lshl_add_u64 v[232:233], v[224:225], 0, s[98:99]
	global_load_lds_dwordx4 v[232:233], off
	s_cmp_lt_u32 s83, 128
	s_mov_b32 s101, 0xd800
	s_cselect_b32 s101, 0x4000, s101
	s_add_i32 m0, s100, s101
	v_lshl_add_u64 v[232:233], v[226:227], 0, s[98:99]
	global_load_lds_dwordx4 v[232:233], off
	ds_read_b128 v[154:157], v133 offset:18432
	ds_read_b128 v[158:161], v133 offset:23040
	ds_read_b128 v[162:165], v133 offset:27648
	ds_read_b128 v[170:173], v133 offset:32256
	s_waitcnt lgkmcnt(3)
	v_mfma_f32_32x32x16_bf16 v[50:65], v[154:157], v[66:69], v[50:65]
	s_waitcnt lgkmcnt(2)
	v_mfma_f32_32x32x16_bf16 v[34:49], v[158:161], v[66:69], v[34:49]
	s_waitcnt lgkmcnt(1)
	v_mfma_f32_32x32x16_bf16 v[18:33], v[162:165], v[66:69], v[18:33]
	ds_read_b128 v[154:157], v133 offset:18464
	ds_read_b128 v[158:161], v133 offset:23072
	ds_read_b128 v[162:165], v133 offset:27680
	ds_read_b128 v[174:177], v133 offset:32288
	s_waitcnt lgkmcnt(4)
	v_mfma_f32_32x32x16_bf16 v[2:17], v[170:173], v[66:69], v[2:17]
	s_waitcnt lgkmcnt(3)
	v_mfma_f32_32x32x16_bf16 v[50:65], v[154:157], v[70:73], v[50:65]
	s_waitcnt lgkmcnt(2)
	v_mfma_f32_32x32x16_bf16 v[34:49], v[158:161], v[70:73], v[34:49]
	s_waitcnt lgkmcnt(1)
	v_mfma_f32_32x32x16_bf16 v[18:33], v[162:165], v[70:73], v[18:33]
	ds_read_b128 v[154:157], v133 offset:18496
	ds_read_b128 v[158:161], v133 offset:23104
	ds_read_b128 v[162:165], v133 offset:27712
	ds_read_b128 v[170:173], v133 offset:32320
	s_waitcnt lgkmcnt(4)
	v_mfma_f32_32x32x16_bf16 v[2:17], v[174:177], v[70:73], v[2:17]
	s_waitcnt lgkmcnt(3)
	v_mfma_f32_32x32x16_bf16 v[50:65], v[154:157], v[74:77], v[50:65]
	s_waitcnt lgkmcnt(2)
	v_mfma_f32_32x32x16_bf16 v[34:49], v[158:161], v[74:77], v[34:49]
	s_waitcnt lgkmcnt(1)
	v_mfma_f32_32x32x16_bf16 v[18:33], v[162:165], v[74:77], v[18:33]
	ds_read_b128 v[154:157], v133 offset:18528
	ds_read_b128 v[158:161], v133 offset:23136
	ds_read_b128 v[162:165], v133 offset:27744
	ds_read_b128 v[174:177], v133 offset:32352
	s_waitcnt lgkmcnt(4)
	v_mfma_f32_32x32x16_bf16 v[2:17], v[170:173], v[74:77], v[2:17]
	s_waitcnt lgkmcnt(3)
	v_mfma_f32_32x32x16_bf16 v[50:65], v[154:157], v[78:81], v[50:65]
	s_waitcnt lgkmcnt(2)
	v_mfma_f32_32x32x16_bf16 v[34:49], v[158:161], v[78:81], v[34:49]
	s_waitcnt lgkmcnt(1)
	v_mfma_f32_32x32x16_bf16 v[18:33], v[162:165], v[78:81], v[18:33]
	s_waitcnt lgkmcnt(0)
	v_mfma_f32_32x32x16_bf16 v[2:17], v[174:177], v[78:81], v[2:17]
	s_bitset1_b32 s0, 7
	v_add_u32_e32 v138, s0, v166
	v_ashrrev_i32_e32 v139, 31, v138
	v_add_u32_e32 v142, s0, v167
	v_lshlrev_b64 v[138:139], 11, v[138:139]
	v_ashrrev_i32_e32 v143, 31, v142
	v_lshl_add_u64 v[138:139], v[140:141], 0, v[138:139]
	v_lshlrev_b64 v[142:143], 11, v[142:143]
	s_waitcnt vmcnt(3)
	s_waitcnt lgkmcnt(0)
	s_barrier
	s_mov_b32 s98, 0x40080
	s_mov_b32 s99, 0
	s_lshl_b32 s100, s83, 4
	s_add_i32 m0, s100, 0x4800
	v_lshl_add_u64 v[232:233], v[222:223], 0, s[98:99]
	global_load_lds_dwordx4 v[232:233], off
	s_add_i32 m0, s100, 0x6800
	v_lshl_add_u64 v[232:233], v[224:225], 0, s[98:99]
	global_load_lds_dwordx4 v[232:233], off
	s_cmp_lt_u32 s83, 128
	s_mov_b32 s101, 0xd800
	s_cselect_b32 s101, 0x8800, s101
	s_add_i32 m0, s100, s101
	v_lshl_add_u64 v[232:233], v[226:227], 0, s[98:99]
	global_load_lds_dwordx4 v[232:233], off
	v_lshl_add_u64 v[140:141], v[140:141], 0, v[142:143]
	ds_read_b128 v[154:157], v133 offset:36864
	ds_read_b128 v[158:161], v133 offset:41472
	ds_read_b128 v[162:165], v133 offset:46080
	ds_read_b128 v[170:173], v133 offset:50688
	s_waitcnt lgkmcnt(3)
	v_mfma_f32_32x32x16_bf16 v[50:65], v[154:157], v[106:109], v[50:65]
	s_waitcnt lgkmcnt(2)
	v_mfma_f32_32x32x16_bf16 v[34:49], v[158:161], v[106:109], v[34:49]
	s_waitcnt lgkmcnt(1)
	v_mfma_f32_32x32x16_bf16 v[18:33], v[162:165], v[106:109], v[18:33]
	ds_read_b128 v[154:157], v133 offset:36896
	ds_read_b128 v[158:161], v133 offset:41504
	ds_read_b128 v[162:165], v133 offset:46112
	ds_read_b128 v[174:177], v133 offset:50720
	s_waitcnt lgkmcnt(4)
	v_mfma_f32_32x32x16_bf16 v[2:17], v[170:173], v[106:109], v[2:17]
	s_waitcnt lgkmcnt(3)
	v_mfma_f32_32x32x16_bf16 v[50:65], v[154:157], v[110:113], v[50:65]
	s_waitcnt lgkmcnt(2)
	v_mfma_f32_32x32x16_bf16 v[34:49], v[158:161], v[110:113], v[34:49]
	s_waitcnt lgkmcnt(1)
	v_mfma_f32_32x32x16_bf16 v[18:33], v[162:165], v[110:113], v[18:33]
	ds_read_b128 v[154:157], v133 offset:36928
	ds_read_b128 v[158:161], v133 offset:41536
	ds_read_b128 v[162:165], v133 offset:46144
	ds_read_b128 v[170:173], v133 offset:50752
	s_waitcnt lgkmcnt(4)
	v_mfma_f32_32x32x16_bf16 v[2:17], v[174:177], v[110:113], v[2:17]
	s_waitcnt lgkmcnt(3)
	v_mfma_f32_32x32x16_bf16 v[50:65], v[154:157], v[122:125], v[50:65]
	s_waitcnt lgkmcnt(2)
	v_mfma_f32_32x32x16_bf16 v[34:49], v[158:161], v[122:125], v[34:49]
	s_waitcnt lgkmcnt(1)
	v_mfma_f32_32x32x16_bf16 v[18:33], v[162:165], v[122:125], v[18:33]
	ds_read_b128 v[154:157], v133 offset:36960
	ds_read_b128 v[158:161], v133 offset:41568
	ds_read_b128 v[162:165], v133 offset:46176
	ds_read_b128 v[174:177], v133 offset:50784
	s_waitcnt lgkmcnt(4)
	v_mfma_f32_32x32x16_bf16 v[2:17], v[170:173], v[122:125], v[2:17]
	s_waitcnt lgkmcnt(3)
	v_mfma_f32_32x32x16_bf16 v[50:65], v[154:157], v[126:129], v[50:65]
	s_waitcnt lgkmcnt(2)
	v_mfma_f32_32x32x16_bf16 v[34:49], v[158:161], v[126:129], v[34:49]
	s_waitcnt lgkmcnt(1)
	v_mfma_f32_32x32x16_bf16 v[18:33], v[162:165], v[126:129], v[18:33]
	s_waitcnt lgkmcnt(0)
	v_mfma_f32_32x32x16_bf16 v[2:17], v[174:177], v[126:129], v[2:17]
	v_add_co_u32_e32 v142, vcc, s84, v144
	s_waitcnt vmcnt(3)
	v_addc_co_u32_e32 v143, vcc, 0, v145, vcc
	global_load_dwordx2 v[172:173], v[142:143], off offset:2048
	global_load_dwordx2 v[174:175], v[136:137], off offset:16
	global_load_dwordx2 v[170:171], v[136:137], off offset:32
	global_load_dwordx2 v[166:167], v[136:137], off offset:48
	global_load_dwordx2 v[164:165], v[136:137], off offset:64
	global_load_dwordx2 v[162:163], v[136:137], off offset:80
	global_load_dwordx2 v[160:161], v[136:137], off offset:96
	global_load_dwordx2 v[158:159], v[136:137], off offset:112
	global_load_dwordx2 v[156:157], v[136:137], off offset:128
	global_load_dwordx2 v[154:155], v[136:137], off offset:144
	global_load_dwordx2 v[152:153], v[136:137], off offset:160
	global_load_dwordx2 v[150:151], v[136:137], off offset:176
	global_load_dwordx2 v[148:149], v[136:137], off offset:192
	global_load_dwordx2 v[146:147], v[136:137], off offset:208
	global_load_dwordx2 v[144:145], v[136:137], off offset:224
	global_load_dwordx2 v[142:143], v[136:137], off offset:240
	v_pk_mul_f32 v[50:51], v[0:1], v[50:51] op_sel_hi:[0,1]
	v_pk_mul_f32 v[52:53], v[0:1], v[52:53] op_sel_hi:[0,1]
	v_pk_mul_f32 v[54:55], v[0:1], v[54:55] op_sel_hi:[0,1]
	v_pk_mul_f32 v[56:57], v[0:1], v[56:57] op_sel_hi:[0,1]
	v_pk_mul_f32 v[34:35], v[0:1], v[34:35] op_sel_hi:[0,1]
	v_pk_mul_f32 v[36:37], v[0:1], v[36:37] op_sel_hi:[0,1]
	v_pk_mul_f32 v[38:39], v[0:1], v[38:39] op_sel_hi:[0,1]
	v_pk_mul_f32 v[40:41], v[0:1], v[40:41] op_sel_hi:[0,1]
	v_pk_mul_f32 v[18:19], v[0:1], v[18:19] op_sel_hi:[0,1]
	v_pk_mul_f32 v[20:21], v[0:1], v[20:21] op_sel_hi:[0,1]
	v_pk_mul_f32 v[22:23], v[0:1], v[22:23] op_sel_hi:[0,1]
	v_pk_mul_f32 v[24:25], v[0:1], v[24:25] op_sel_hi:[0,1]
	v_pk_mul_f32 v[2:3], v[0:1], v[2:3] op_sel_hi:[0,1]
	v_pk_mul_f32 v[4:5], v[0:1], v[4:5] op_sel_hi:[0,1]
	v_pk_mul_f32 v[6:7], v[0:1], v[6:7] op_sel_hi:[0,1]
	v_pk_mul_f32 v[8:9], v[0:1], v[8:9] op_sel_hi:[0,1]
	s_waitcnt vmcnt(15)
	v_lshlrev_b32_e32 v176, 16, v172
	v_mul_f32_e32 v131, 0xbfb8aa3b, v176
	v_exp_f32_e32 v131, v131
	v_and_b32_e32 v177, 0xffff0000, v172
	v_lshlrev_b32_e32 v172, 16, v173
	v_and_b32_e32 v173, 0xffff0000, v173
	v_add_f32_e32 v131, 1.0, v131
	v_rcp_f32_e32 v178, v131
	v_mul_f32_e32 v131, 0xbfb8aa3b, v177
	v_exp_f32_e32 v131, v131
	s_nop 0
	v_add_f32_e32 v131, 1.0, v131
	v_rcp_f32_e32 v179, v131
	v_ashrrev_i32_e32 v131, 31, v130
	v_lshl_add_u64 v[130:131], v[130:131], 1, v[168:169]
	v_pk_mul_f32 v[176:177], v[178:179], v[176:177]
	s_nop 0
	v_pk_mul_f32 v[50:51], v[50:51], v[176:177]
	s_nop 0
	v_cvt_pk_bf16_f32 v50, v50, v51
	v_mul_f32_e32 v51, 0xbfb8aa3b, v172
	v_exp_f32_e32 v51, v51
	s_nop 0
	v_add_f32_e32 v51, 1.0, v51
	v_rcp_f32_e32 v176, v51
	v_mul_f32_e32 v51, 0xbfb8aa3b, v173
	v_exp_f32_e32 v51, v51
	s_nop 0
	v_add_f32_e32 v51, 1.0, v51
	v_rcp_f32_e32 v177, v51
	s_nop 0
	v_pk_mul_f32 v[172:173], v[176:177], v[172:173]
	s_nop 0
	v_pk_mul_f32 v[52:53], v[52:53], v[172:173]
	s_nop 0
	v_cvt_pk_bf16_f32 v51, v52, v53
	global_store_dwordx2 v[130:131], v[50:51], off
	s_waitcnt vmcnt(15)
	v_lshlrev_b32_e32 v50, 16, v174
	v_and_b32_e32 v51, 0xffff0000, v174
	v_mul_f32_e32 v52, 0xbfb8aa3b, v50
	v_mul_f32_e32 v53, 0xbfb8aa3b, v51
	v_exp_f32_e32 v52, v52
	v_exp_f32_e32 v53, v53
	v_add_f32_e32 v52, 1.0, v52
	v_add_f32_e32 v53, 1.0, v53
	v_rcp_f32_e32 v52, v52
	v_rcp_f32_e32 v53, v53
	s_nop 0
	v_pk_mul_f32 v[50:51], v[52:53], v[50:51]
	s_nop 0
	v_pk_mul_f32 v[50:51], v[54:55], v[50:51]
	v_lshlrev_b32_e32 v52, 16, v175
	v_cvt_pk_bf16_f32 v50, v50, v51
	v_mul_f32_e32 v51, 0xbfb8aa3b, v52
	v_exp_f32_e32 v51, v51
	v_and_b32_e32 v53, 0xffff0000, v175
	v_add_f32_e32 v51, 1.0, v51
	v_rcp_f32_e32 v54, v51
	v_mul_f32_e32 v51, 0xbfb8aa3b, v53
	v_exp_f32_e32 v51, v51
	s_nop 0
	v_add_f32_e32 v51, 1.0, v51
	v_rcp_f32_e32 v55, v51
	s_nop 0
	v_pk_mul_f32 v[52:53], v[54:55], v[52:53]
	s_nop 0
	v_pk_mul_f32 v[52:53], v[56:57], v[52:53]
	v_pk_mul_f32 v[54:55], v[0:1], v[58:59] op_sel_hi:[0,1]
	v_cvt_pk_bf16_f32 v51, v52, v53
	global_store_dwordx2 v[130:131], v[50:51], off offset:16
	s_waitcnt vmcnt(15)
	v_lshlrev_b32_e32 v50, 16, v170
	v_and_b32_e32 v51, 0xffff0000, v170
	v_mul_f32_e32 v52, 0xbfb8aa3b, v50
	v_mul_f32_e32 v53, 0xbfb8aa3b, v51
	v_exp_f32_e32 v52, v52
	v_exp_f32_e32 v53, v53
	v_pk_mul_f32 v[56:57], v[0:1], v[60:61] op_sel_hi:[0,1]
	v_add_f32_e32 v52, 1.0, v52
	v_add_f32_e32 v53, 1.0, v53
	v_rcp_f32_e32 v52, v52
	v_rcp_f32_e32 v53, v53
	s_nop 0
	v_pk_mul_f32 v[50:51], v[52:53], v[50:51]
	s_nop 0
	v_pk_mul_f32 v[50:51], v[54:55], v[50:51]
	v_lshlrev_b32_e32 v52, 16, v171
	v_cvt_pk_bf16_f32 v50, v50, v51
	v_mul_f32_e32 v51, 0xbfb8aa3b, v52
	v_exp_f32_e32 v51, v51
	v_and_b32_e32 v53, 0xffff0000, v171
	v_add_f32_e32 v51, 1.0, v51
	v_rcp_f32_e32 v54, v51
	v_mul_f32_e32 v51, 0xbfb8aa3b, v53
	v_exp_f32_e32 v51, v51
	s_nop 0
	v_add_f32_e32 v51, 1.0, v51
	v_rcp_f32_e32 v55, v51
	s_nop 0
	v_pk_mul_f32 v[52:53], v[54:55], v[52:53]
	s_nop 0
	v_pk_mul_f32 v[52:53], v[56:57], v[52:53]
	v_pk_mul_f32 v[54:55], v[0:1], v[62:63] op_sel_hi:[0,1]
	v_cvt_pk_bf16_f32 v51, v52, v53
	global_store_dwordx2 v[130:131], v[50:51], off offset:32
	s_waitcnt vmcnt(15)
	v_lshlrev_b32_e32 v50, 16, v166
	v_and_b32_e32 v51, 0xffff0000, v166
	v_mul_f32_e32 v52, 0xbfb8aa3b, v50
	v_mul_f32_e32 v53, 0xbfb8aa3b, v51
	v_exp_f32_e32 v52, v52
	v_exp_f32_e32 v53, v53
	v_pk_mul_f32 v[56:57], v[0:1], v[64:65] op_sel_hi:[0,1]
	v_add_f32_e32 v52, 1.0, v52
	v_add_f32_e32 v53, 1.0, v53
	v_rcp_f32_e32 v52, v52
	v_rcp_f32_e32 v53, v53
	s_nop 0
	v_pk_mul_f32 v[50:51], v[52:53], v[50:51]
	s_nop 0
	v_pk_mul_f32 v[50:51], v[54:55], v[50:51]
	v_lshlrev_b32_e32 v52, 16, v167
	v_cvt_pk_bf16_f32 v50, v50, v51
	v_mul_f32_e32 v51, 0xbfb8aa3b, v52
	v_exp_f32_e32 v51, v51
	v_and_b32_e32 v53, 0xffff0000, v167
	v_add_f32_e32 v51, 1.0, v51
	v_rcp_f32_e32 v54, v51
	v_mul_f32_e32 v51, 0xbfb8aa3b, v53
	v_exp_f32_e32 v51, v51
	s_nop 0
	v_add_f32_e32 v51, 1.0, v51
	v_rcp_f32_e32 v55, v51
	s_nop 0
	v_pk_mul_f32 v[52:53], v[54:55], v[52:53]
	s_nop 0
	v_pk_mul_f32 v[52:53], v[56:57], v[52:53]
	s_nop 0
	v_cvt_pk_bf16_f32 v51, v52, v53
	global_store_dwordx2 v[130:131], v[50:51], off offset:48
	s_waitcnt vmcnt(15)
	v_lshlrev_b32_e32 v50, 16, v164
	v_and_b32_e32 v51, 0xffff0000, v164
	v_mul_f32_e32 v52, 0xbfb8aa3b, v50
	v_mul_f32_e32 v53, 0xbfb8aa3b, v51
	v_exp_f32_e32 v52, v52
	v_exp_f32_e32 v53, v53
	v_add_f32_e32 v52, 1.0, v52
	v_add_f32_e32 v53, 1.0, v53
	v_rcp_f32_e32 v52, v52
	v_rcp_f32_e32 v53, v53
	s_nop 0
	v_pk_mul_f32 v[50:51], v[52:53], v[50:51]
	s_nop 0
	v_pk_mul_f32 v[34:35], v[34:35], v[50:51]
	v_lshlrev_b32_e32 v50, 16, v165
	v_cvt_pk_bf16_f32 v34, v34, v35
	v_mul_f32_e32 v35, 0xbfb8aa3b, v50
	v_exp_f32_e32 v35, v35
	v_and_b32_e32 v51, 0xffff0000, v165
	v_add_f32_e32 v35, 1.0, v35
	v_rcp_f32_e32 v52, v35
	v_mul_f32_e32 v35, 0xbfb8aa3b, v51
	v_exp_f32_e32 v35, v35
	s_nop 0
	v_add_f32_e32 v35, 1.0, v35
	v_rcp_f32_e32 v53, v35
	s_nop 0
	v_pk_mul_f32 v[50:51], v[52:53], v[50:51]
	s_nop 0
	v_pk_mul_f32 v[36:37], v[36:37], v[50:51]
	s_nop 0
	v_cvt_pk_bf16_f32 v35, v36, v37
	global_store_dwordx2 v[130:131], v[34:35], off offset:64
	s_waitcnt vmcnt(15)
	v_lshlrev_b32_e32 v34, 16, v162
	v_and_b32_e32 v35, 0xffff0000, v162
	v_mul_f32_e32 v36, 0xbfb8aa3b, v34
	v_mul_f32_e32 v37, 0xbfb8aa3b, v35
	v_exp_f32_e32 v36, v36
	v_exp_f32_e32 v37, v37
	v_add_f32_e32 v36, 1.0, v36
	v_add_f32_e32 v37, 1.0, v37
	v_rcp_f32_e32 v36, v36
	v_rcp_f32_e32 v37, v37
	s_nop 0
	v_pk_mul_f32 v[34:35], v[36:37], v[34:35]
	s_nop 0
	v_pk_mul_f32 v[34:35], v[38:39], v[34:35]
	v_lshlrev_b32_e32 v36, 16, v163
	v_cvt_pk_bf16_f32 v34, v34, v35
	v_mul_f32_e32 v35, 0xbfb8aa3b, v36
	v_exp_f32_e32 v35, v35
	v_and_b32_e32 v37, 0xffff0000, v163
	v_add_f32_e32 v35, 1.0, v35
	v_rcp_f32_e32 v38, v35
	v_mul_f32_e32 v35, 0xbfb8aa3b, v37
	v_exp_f32_e32 v35, v35
	s_nop 0
	v_add_f32_e32 v35, 1.0, v35
	v_rcp_f32_e32 v39, v35
	s_nop 0
	v_pk_mul_f32 v[36:37], v[38:39], v[36:37]
	s_nop 0
	v_pk_mul_f32 v[36:37], v[40:41], v[36:37]
	v_pk_mul_f32 v[38:39], v[0:1], v[42:43] op_sel_hi:[0,1]
	v_cvt_pk_bf16_f32 v35, v36, v37
	global_store_dwordx2 v[130:131], v[34:35], off offset:80
	s_waitcnt vmcnt(15)
	v_lshlrev_b32_e32 v34, 16, v160
	v_and_b32_e32 v35, 0xffff0000, v160
	v_mul_f32_e32 v36, 0xbfb8aa3b, v34
	v_mul_f32_e32 v37, 0xbfb8aa3b, v35
	v_exp_f32_e32 v36, v36
	v_exp_f32_e32 v37, v37
	v_pk_mul_f32 v[40:41], v[0:1], v[44:45] op_sel_hi:[0,1]
	v_add_f32_e32 v36, 1.0, v36
	v_add_f32_e32 v37, 1.0, v37
	v_rcp_f32_e32 v36, v36
	v_rcp_f32_e32 v37, v37
	s_nop 0
	v_pk_mul_f32 v[34:35], v[36:37], v[34:35]
	s_nop 0
	v_pk_mul_f32 v[34:35], v[38:39], v[34:35]
	v_lshlrev_b32_e32 v36, 16, v161
	v_cvt_pk_bf16_f32 v34, v34, v35
	v_mul_f32_e32 v35, 0xbfb8aa3b, v36
	v_exp_f32_e32 v35, v35
	v_and_b32_e32 v37, 0xffff0000, v161
	v_add_f32_e32 v35, 1.0, v35
	v_rcp_f32_e32 v38, v35
	v_mul_f32_e32 v35, 0xbfb8aa3b, v37
	v_exp_f32_e32 v35, v35
	s_nop 0
	v_add_f32_e32 v35, 1.0, v35
	v_rcp_f32_e32 v39, v35
	s_nop 0
	v_pk_mul_f32 v[36:37], v[38:39], v[36:37]
	s_nop 0
	v_pk_mul_f32 v[36:37], v[40:41], v[36:37]
	v_pk_mul_f32 v[38:39], v[0:1], v[46:47] op_sel_hi:[0,1]
	v_cvt_pk_bf16_f32 v35, v36, v37
	global_store_dwordx2 v[130:131], v[34:35], off offset:96
	s_waitcnt vmcnt(15)
	v_lshlrev_b32_e32 v34, 16, v158
	v_and_b32_e32 v35, 0xffff0000, v158
	v_mul_f32_e32 v36, 0xbfb8aa3b, v34
	v_mul_f32_e32 v37, 0xbfb8aa3b, v35
	v_exp_f32_e32 v36, v36
	v_exp_f32_e32 v37, v37
	v_pk_mul_f32 v[40:41], v[0:1], v[48:49] op_sel_hi:[0,1]
	v_add_f32_e32 v36, 1.0, v36
	v_add_f32_e32 v37, 1.0, v37
	v_rcp_f32_e32 v36, v36
	v_rcp_f32_e32 v37, v37
	s_nop 0
	v_pk_mul_f32 v[34:35], v[36:37], v[34:35]
	s_nop 0
	v_pk_mul_f32 v[34:35], v[38:39], v[34:35]
	v_lshlrev_b32_e32 v36, 16, v159
	v_cvt_pk_bf16_f32 v34, v34, v35
	v_mul_f32_e32 v35, 0xbfb8aa3b, v36
	v_exp_f32_e32 v35, v35
	v_and_b32_e32 v37, 0xffff0000, v159
	v_add_f32_e32 v35, 1.0, v35
	v_rcp_f32_e32 v38, v35
	v_mul_f32_e32 v35, 0xbfb8aa3b, v37
	v_exp_f32_e32 v35, v35
	s_nop 0
	v_add_f32_e32 v35, 1.0, v35
	v_rcp_f32_e32 v39, v35
	s_nop 0
	v_pk_mul_f32 v[36:37], v[38:39], v[36:37]
	s_nop 0
	v_pk_mul_f32 v[36:37], v[40:41], v[36:37]
	s_nop 0
	v_cvt_pk_bf16_f32 v35, v36, v37
	global_store_dwordx2 v[130:131], v[34:35], off offset:112
	s_waitcnt vmcnt(15)
	v_lshlrev_b32_e32 v34, 16, v156
	v_and_b32_e32 v35, 0xffff0000, v156
	v_mul_f32_e32 v36, 0xbfb8aa3b, v34
	v_mul_f32_e32 v37, 0xbfb8aa3b, v35
	v_exp_f32_e32 v36, v36
	v_exp_f32_e32 v37, v37
	v_add_f32_e32 v36, 1.0, v36
	v_add_f32_e32 v37, 1.0, v37
	v_rcp_f32_e32 v36, v36
	v_rcp_f32_e32 v37, v37
	s_nop 0
	v_pk_mul_f32 v[34:35], v[36:37], v[34:35]
	s_nop 0
	v_pk_mul_f32 v[18:19], v[18:19], v[34:35]
	v_lshlrev_b32_e32 v34, 16, v157
	v_cvt_pk_bf16_f32 v18, v18, v19
	v_mul_f32_e32 v19, 0xbfb8aa3b, v34
	v_exp_f32_e32 v19, v19
	v_and_b32_e32 v35, 0xffff0000, v157
	v_add_f32_e32 v19, 1.0, v19
	v_rcp_f32_e32 v36, v19
	v_mul_f32_e32 v19, 0xbfb8aa3b, v35
	v_exp_f32_e32 v19, v19
	s_nop 0
	v_add_f32_e32 v19, 1.0, v19
	v_rcp_f32_e32 v37, v19
	s_nop 0
	v_pk_mul_f32 v[34:35], v[36:37], v[34:35]
	s_nop 0
	v_pk_mul_f32 v[20:21], v[20:21], v[34:35]
	s_nop 0
	v_cvt_pk_bf16_f32 v19, v20, v21
	global_store_dwordx2 v[130:131], v[18:19], off offset:128
	s_waitcnt vmcnt(15)
	v_lshlrev_b32_e32 v18, 16, v154
	v_and_b32_e32 v19, 0xffff0000, v154
	v_mul_f32_e32 v20, 0xbfb8aa3b, v18
	v_mul_f32_e32 v21, 0xbfb8aa3b, v19
	v_exp_f32_e32 v20, v20
	v_exp_f32_e32 v21, v21
	v_add_f32_e32 v20, 1.0, v20
	v_add_f32_e32 v21, 1.0, v21
	v_rcp_f32_e32 v20, v20
	v_rcp_f32_e32 v21, v21
	s_nop 0
	v_pk_mul_f32 v[18:19], v[20:21], v[18:19]
	s_nop 0
	v_pk_mul_f32 v[18:19], v[22:23], v[18:19]
	v_lshlrev_b32_e32 v20, 16, v155
	v_cvt_pk_bf16_f32 v18, v18, v19
	v_mul_f32_e32 v19, 0xbfb8aa3b, v20
	v_exp_f32_e32 v19, v19
	v_and_b32_e32 v21, 0xffff0000, v155
	v_add_f32_e32 v19, 1.0, v19
	v_rcp_f32_e32 v22, v19
	v_mul_f32_e32 v19, 0xbfb8aa3b, v21
	v_exp_f32_e32 v19, v19
	s_nop 0
	v_add_f32_e32 v19, 1.0, v19
	v_rcp_f32_e32 v23, v19
	s_nop 0
	v_pk_mul_f32 v[20:21], v[22:23], v[20:21]
	s_nop 0
	v_pk_mul_f32 v[20:21], v[24:25], v[20:21]
	v_pk_mul_f32 v[22:23], v[0:1], v[26:27] op_sel_hi:[0,1]
	v_cvt_pk_bf16_f32 v19, v20, v21
	global_store_dwordx2 v[130:131], v[18:19], off offset:144
	s_waitcnt vmcnt(15)
	v_lshlrev_b32_e32 v18, 16, v152
	v_and_b32_e32 v19, 0xffff0000, v152
	v_mul_f32_e32 v20, 0xbfb8aa3b, v18
	v_mul_f32_e32 v21, 0xbfb8aa3b, v19
	v_exp_f32_e32 v20, v20
	v_exp_f32_e32 v21, v21
	v_pk_mul_f32 v[24:25], v[0:1], v[28:29] op_sel_hi:[0,1]
	v_add_f32_e32 v20, 1.0, v20
	v_add_f32_e32 v21, 1.0, v21
	v_rcp_f32_e32 v20, v20
	v_rcp_f32_e32 v21, v21
	s_nop 0
	v_pk_mul_f32 v[18:19], v[20:21], v[18:19]
	s_nop 0
	v_pk_mul_f32 v[18:19], v[22:23], v[18:19]
	v_lshlrev_b32_e32 v20, 16, v153
	v_cvt_pk_bf16_f32 v18, v18, v19
	v_mul_f32_e32 v19, 0xbfb8aa3b, v20
	v_exp_f32_e32 v19, v19
	v_and_b32_e32 v21, 0xffff0000, v153
	v_add_f32_e32 v19, 1.0, v19
	v_rcp_f32_e32 v22, v19
	v_mul_f32_e32 v19, 0xbfb8aa3b, v21
	v_exp_f32_e32 v19, v19
	s_nop 0
	v_add_f32_e32 v19, 1.0, v19
	v_rcp_f32_e32 v23, v19
	s_nop 0
	v_pk_mul_f32 v[20:21], v[22:23], v[20:21]
	s_nop 0
	v_pk_mul_f32 v[20:21], v[24:25], v[20:21]
	v_pk_mul_f32 v[22:23], v[0:1], v[30:31] op_sel_hi:[0,1]
	v_cvt_pk_bf16_f32 v19, v20, v21
	global_store_dwordx2 v[130:131], v[18:19], off offset:160
	s_waitcnt vmcnt(15)
	v_lshlrev_b32_e32 v18, 16, v150
	v_and_b32_e32 v19, 0xffff0000, v150
	v_mul_f32_e32 v20, 0xbfb8aa3b, v18
	v_mul_f32_e32 v21, 0xbfb8aa3b, v19
	v_exp_f32_e32 v20, v20
	v_exp_f32_e32 v21, v21
	v_pk_mul_f32 v[24:25], v[0:1], v[32:33] op_sel_hi:[0,1]
	v_add_f32_e32 v20, 1.0, v20
	v_add_f32_e32 v21, 1.0, v21
	v_rcp_f32_e32 v20, v20
	v_rcp_f32_e32 v21, v21
	s_nop 0
	v_pk_mul_f32 v[18:19], v[20:21], v[18:19]
	s_nop 0
	v_pk_mul_f32 v[18:19], v[22:23], v[18:19]
	v_lshlrev_b32_e32 v20, 16, v151
	v_cvt_pk_bf16_f32 v18, v18, v19
	v_mul_f32_e32 v19, 0xbfb8aa3b, v20
	v_exp_f32_e32 v19, v19
	v_and_b32_e32 v21, 0xffff0000, v151
	v_add_f32_e32 v19, 1.0, v19
	v_rcp_f32_e32 v22, v19
	v_mul_f32_e32 v19, 0xbfb8aa3b, v21
	v_exp_f32_e32 v19, v19
	s_nop 0
	v_add_f32_e32 v19, 1.0, v19
	v_rcp_f32_e32 v23, v19
	s_nop 0
	v_pk_mul_f32 v[20:21], v[22:23], v[20:21]
	s_nop 0
	v_pk_mul_f32 v[20:21], v[24:25], v[20:21]
	s_nop 0
	v_cvt_pk_bf16_f32 v19, v20, v21
	global_store_dwordx2 v[130:131], v[18:19], off offset:176
	s_waitcnt vmcnt(15)
	v_lshlrev_b32_e32 v18, 16, v148
	v_and_b32_e32 v19, 0xffff0000, v148
	v_mul_f32_e32 v20, 0xbfb8aa3b, v18
	v_mul_f32_e32 v21, 0xbfb8aa3b, v19
	v_exp_f32_e32 v20, v20
	v_exp_f32_e32 v21, v21
	v_add_f32_e32 v20, 1.0, v20
	v_add_f32_e32 v21, 1.0, v21
	v_rcp_f32_e32 v20, v20
	v_rcp_f32_e32 v21, v21
	s_nop 0
	v_pk_mul_f32 v[18:19], v[20:21], v[18:19]
	s_nop 0
	v_pk_mul_f32 v[2:3], v[2:3], v[18:19]
	v_lshlrev_b32_e32 v18, 16, v149
	v_cvt_pk_bf16_f32 v2, v2, v3
	v_mul_f32_e32 v3, 0xbfb8aa3b, v18
	v_exp_f32_e32 v3, v3
	v_and_b32_e32 v19, 0xffff0000, v149
	v_add_f32_e32 v3, 1.0, v3
	v_rcp_f32_e32 v20, v3
	v_mul_f32_e32 v3, 0xbfb8aa3b, v19
	v_exp_f32_e32 v3, v3
	s_nop 0
	v_add_f32_e32 v3, 1.0, v3
	v_rcp_f32_e32 v21, v3
	s_nop 0
	v_pk_mul_f32 v[18:19], v[20:21], v[18:19]
	s_nop 0
	v_pk_mul_f32 v[4:5], v[4:5], v[18:19]
	s_nop 0
	v_cvt_pk_bf16_f32 v3, v4, v5
	global_store_dwordx2 v[130:131], v[2:3], off offset:192
	s_waitcnt vmcnt(15)
	v_lshlrev_b32_e32 v2, 16, v146
	v_and_b32_e32 v3, 0xffff0000, v146
	v_mul_f32_e32 v4, 0xbfb8aa3b, v2
	v_mul_f32_e32 v5, 0xbfb8aa3b, v3
	v_exp_f32_e32 v4, v4
	v_exp_f32_e32 v5, v5
	v_add_f32_e32 v4, 1.0, v4
	v_add_f32_e32 v5, 1.0, v5
	v_rcp_f32_e32 v4, v4
	v_rcp_f32_e32 v5, v5
	s_nop 0
	v_pk_mul_f32 v[2:3], v[4:5], v[2:3]
	s_nop 0
	v_pk_mul_f32 v[2:3], v[6:7], v[2:3]
	v_lshlrev_b32_e32 v4, 16, v147
	v_cvt_pk_bf16_f32 v2, v2, v3
	v_mul_f32_e32 v3, 0xbfb8aa3b, v4
	v_exp_f32_e32 v3, v3
	v_and_b32_e32 v5, 0xffff0000, v147
	v_add_f32_e32 v3, 1.0, v3
	v_rcp_f32_e32 v6, v3
	v_mul_f32_e32 v3, 0xbfb8aa3b, v5
	v_exp_f32_e32 v3, v3
	s_nop 0
	v_add_f32_e32 v3, 1.0, v3
	v_rcp_f32_e32 v7, v3
	s_nop 0
	v_pk_mul_f32 v[4:5], v[6:7], v[4:5]
	s_nop 0
	v_pk_mul_f32 v[4:5], v[8:9], v[4:5]
	v_pk_mul_f32 v[6:7], v[0:1], v[10:11] op_sel_hi:[0,1]
	v_cvt_pk_bf16_f32 v3, v4, v5
	global_store_dwordx2 v[130:131], v[2:3], off offset:208
	s_waitcnt vmcnt(15)
	v_lshlrev_b32_e32 v2, 16, v144
	v_and_b32_e32 v3, 0xffff0000, v144
	v_mul_f32_e32 v4, 0xbfb8aa3b, v2
	v_mul_f32_e32 v5, 0xbfb8aa3b, v3
	v_exp_f32_e32 v4, v4
	v_exp_f32_e32 v5, v5
	v_pk_mul_f32 v[8:9], v[0:1], v[12:13] op_sel_hi:[0,1]
	v_add_f32_e32 v4, 1.0, v4
	v_add_f32_e32 v5, 1.0, v5
	v_rcp_f32_e32 v4, v4
	v_rcp_f32_e32 v5, v5
	s_nop 0
	v_pk_mul_f32 v[2:3], v[4:5], v[2:3]
	s_nop 0
	v_pk_mul_f32 v[2:3], v[6:7], v[2:3]
	v_lshlrev_b32_e32 v4, 16, v145
	v_cvt_pk_bf16_f32 v2, v2, v3
	v_mul_f32_e32 v3, 0xbfb8aa3b, v4
	v_exp_f32_e32 v3, v3
	v_and_b32_e32 v5, 0xffff0000, v145
	v_add_f32_e32 v3, 1.0, v3
	v_rcp_f32_e32 v6, v3
	v_mul_f32_e32 v3, 0xbfb8aa3b, v5
	v_exp_f32_e32 v3, v3
	s_nop 0
	v_add_f32_e32 v3, 1.0, v3
	v_rcp_f32_e32 v7, v3
	s_nop 0
	v_pk_mul_f32 v[4:5], v[6:7], v[4:5]
	s_nop 0
	v_pk_mul_f32 v[4:5], v[8:9], v[4:5]
	v_pk_mul_f32 v[6:7], v[0:1], v[14:15] op_sel_hi:[0,1]
	v_cvt_pk_bf16_f32 v3, v4, v5
	global_store_dwordx2 v[130:131], v[2:3], off offset:224
	s_waitcnt vmcnt(15)
	v_lshlrev_b32_e32 v2, 16, v142
	v_and_b32_e32 v3, 0xffff0000, v142
	v_mul_f32_e32 v4, 0xbfb8aa3b, v2
	v_mul_f32_e32 v5, 0xbfb8aa3b, v3
	v_exp_f32_e32 v4, v4
	v_exp_f32_e32 v5, v5
	v_pk_mul_f32 v[8:9], v[0:1], v[16:17] op_sel_hi:[0,1]
	v_add_f32_e32 v4, 1.0, v4
	v_add_f32_e32 v5, 1.0, v5
	v_rcp_f32_e32 v4, v4
	v_rcp_f32_e32 v5, v5
	s_nop 0
	v_pk_mul_f32 v[2:3], v[4:5], v[2:3]
	s_nop 0
	v_pk_mul_f32 v[2:3], v[6:7], v[2:3]
	v_lshlrev_b32_e32 v4, 16, v143
	v_cvt_pk_bf16_f32 v2, v2, v3
	v_mul_f32_e32 v3, 0xbfb8aa3b, v4
	v_exp_f32_e32 v3, v3
	v_and_b32_e32 v5, 0xffff0000, v143
	v_add_f32_e32 v3, 1.0, v3
	v_rcp_f32_e32 v6, v3
	v_mul_f32_e32 v3, 0xbfb8aa3b, v5
	v_exp_f32_e32 v3, v3
	s_nop 0
	v_add_f32_e32 v3, 1.0, v3
	v_rcp_f32_e32 v7, v3
	s_nop 0
	v_pk_mul_f32 v[4:5], v[6:7], v[4:5]
	s_nop 0
	v_pk_mul_f32 v[4:5], v[8:9], v[4:5]
	s_nop 0
	v_cvt_pk_bf16_f32 v3, v4, v5
	global_store_dwordx2 v[130:131], v[2:3], off offset:240
	s_waitcnt lgkmcnt(0)
	s_barrier
	s_mov_b32 s98, 0x40100
	s_mov_b32 s99, 0
	s_lshl_b32 s100, s83, 4
	s_add_i32 m0, s100, 0x9000
	v_lshl_add_u64 v[232:233], v[222:223], 0, s[98:99]
	global_load_lds_dwordx4 v[232:233], off
	s_add_i32 m0, s100, 0xb000
	v_lshl_add_u64 v[232:233], v[224:225], 0, s[98:99]
	global_load_lds_dwordx4 v[232:233], off
	s_cmp_lt_u32 s83, 128
	s_mov_b32 s101, 0xd800
	s_cselect_b32 s101, 0xd000, s101
	s_add_i32 m0, s100, s101
	v_lshl_add_u64 v[232:233], v[226:227], 0, s[98:99]
	global_load_lds_dwordx4 v[232:233], off
	ds_read_b128 v[2:5], v133
	ds_read_b128 v[6:9], v133 offset:4608
	ds_read_b128 v[10:13], v133 offset:9216
	ds_read_b128 v[14:17], v133 offset:13824
	ds_read_b128 v[150:153], v133 offset:32
	ds_read_b128 v[154:157], v133 offset:4640
	ds_read_b128 v[158:161], v133 offset:9248
	ds_read_b128 v[162:165], v133 offset:13856
	s_waitcnt lgkmcnt(7)
	v_mfma_f32_32x32x16_bf16 v[50:65], v[2:5], v[114:117], 0
	s_waitcnt lgkmcnt(6)
	v_mfma_f32_32x32x16_bf16 v[34:49], v[6:9], v[114:117], 0
	s_waitcnt lgkmcnt(5)
	v_mfma_f32_32x32x16_bf16 v[18:33], v[10:13], v[114:117], 0
	s_waitcnt lgkmcnt(4)
	v_mfma_f32_32x32x16_bf16 v[2:17], v[14:17], v[114:117], 0
	s_waitcnt lgkmcnt(3)
	v_mfma_f32_32x32x16_bf16 v[50:65], v[150:153], v[118:121], v[50:65]
	s_waitcnt lgkmcnt(2)
	v_mfma_f32_32x32x16_bf16 v[34:49], v[154:157], v[118:121], v[34:49]
	s_waitcnt lgkmcnt(1)
	v_mfma_f32_32x32x16_bf16 v[18:33], v[158:161], v[118:121], v[18:33]
	ds_read_b128 v[114:117], v133 offset:64
	ds_read_b128 v[150:153], v133 offset:4672
	ds_read_b128 v[154:157], v133 offset:9280
	ds_read_b128 v[158:161], v133 offset:13888
	s_waitcnt lgkmcnt(4)
	v_mfma_f32_32x32x16_bf16 v[2:17], v[162:165], v[118:121], v[2:17]
	s_waitcnt lgkmcnt(3)
	v_mfma_f32_32x32x16_bf16 v[50:65], v[114:117], v[82:85], v[50:65]
	s_waitcnt lgkmcnt(2)
	v_mfma_f32_32x32x16_bf16 v[34:49], v[150:153], v[82:85], v[34:49]
	s_waitcnt lgkmcnt(1)
	v_mfma_f32_32x32x16_bf16 v[18:33], v[154:157], v[82:85], v[18:33]
	ds_read_b128 v[114:117], v133 offset:96
	ds_read_b128 v[118:121], v133 offset:4704
	ds_read_b128 v[150:153], v133 offset:9312
	ds_read_b128 v[154:157], v133 offset:13920
	s_waitcnt lgkmcnt(4)
	v_mfma_f32_32x32x16_bf16 v[2:17], v[158:161], v[82:85], v[2:17]
	s_waitcnt lgkmcnt(3)
	v_mfma_f32_32x32x16_bf16 v[50:65], v[114:117], v[86:89], v[50:65]
	s_waitcnt lgkmcnt(2)
	v_mfma_f32_32x32x16_bf16 v[34:49], v[118:121], v[86:89], v[34:49]
	s_waitcnt lgkmcnt(1)
	v_mfma_f32_32x32x16_bf16 v[18:33], v[150:153], v[86:89], v[18:33]
	s_waitcnt lgkmcnt(0)
	v_mfma_f32_32x32x16_bf16 v[2:17], v[154:157], v[86:89], v[2:17]
	s_waitcnt vmcnt(3)
	s_waitcnt lgkmcnt(0)
	s_barrier
	s_mov_b32 s98, 0x40180
	s_mov_b32 s99, 0
	s_lshl_b32 s100, s83, 4
	s_add_i32 m0, s100, 0x0
	v_lshl_add_u64 v[232:233], v[222:223], 0, s[98:99]
	global_load_lds_dwordx4 v[232:233], off
	s_add_i32 m0, s100, 0x2000
	v_lshl_add_u64 v[232:233], v[224:225], 0, s[98:99]
	global_load_lds_dwordx4 v[232:233], off
	s_cmp_lt_u32 s83, 128
	s_mov_b32 s101, 0xd800
	s_cselect_b32 s101, 0x4000, s101
	s_add_i32 m0, s100, s101
	v_lshl_add_u64 v[232:233], v[226:227], 0, s[98:99]
	global_load_lds_dwordx4 v[232:233], off
	ds_read_b128 v[114:117], v133 offset:18432
	ds_read_b128 v[118:121], v133 offset:23040
	ds_read_b128 v[142:145], v133 offset:27648
	ds_read_b128 v[146:149], v133 offset:32256
	s_waitcnt lgkmcnt(3)
	v_mfma_f32_32x32x16_bf16 v[50:65], v[114:117], v[90:93], v[50:65]
	s_waitcnt lgkmcnt(2)
	v_mfma_f32_32x32x16_bf16 v[34:49], v[118:121], v[90:93], v[34:49]
	s_waitcnt lgkmcnt(1)
	v_mfma_f32_32x32x16_bf16 v[18:33], v[142:145], v[90:93], v[18:33]
	ds_read_b128 v[114:117], v133 offset:18464
	ds_read_b128 v[118:121], v133 offset:23072
	ds_read_b128 v[142:145], v133 offset:27680
	ds_read_b128 v[150:153], v133 offset:32288
	s_waitcnt lgkmcnt(4)
	v_mfma_f32_32x32x16_bf16 v[2:17], v[146:149], v[90:93], v[2:17]
	s_waitcnt lgkmcnt(3)
	v_mfma_f32_32x32x16_bf16 v[50:65], v[114:117], v[94:97], v[50:65]
	s_waitcnt lgkmcnt(2)
	v_mfma_f32_32x32x16_bf16 v[34:49], v[118:121], v[94:97], v[34:49]
	s_waitcnt lgkmcnt(1)
	v_mfma_f32_32x32x16_bf16 v[18:33], v[142:145], v[94:97], v[18:33]
	ds_read_b128 v[90:93], v133 offset:18496
	ds_read_b128 v[114:117], v133 offset:23104
	ds_read_b128 v[118:121], v133 offset:27712
	ds_read_b128 v[142:145], v133 offset:32320
	s_waitcnt lgkmcnt(4)
	v_mfma_f32_32x32x16_bf16 v[2:17], v[150:153], v[94:97], v[2:17]
	s_waitcnt lgkmcnt(3)
	v_mfma_f32_32x32x16_bf16 v[50:65], v[90:93], v[98:101], v[50:65]
	s_waitcnt lgkmcnt(2)
	v_mfma_f32_32x32x16_bf16 v[34:49], v[114:117], v[98:101], v[34:49]
	s_waitcnt lgkmcnt(1)
	v_mfma_f32_32x32x16_bf16 v[18:33], v[118:121], v[98:101], v[18:33]
	ds_read_b128 v[90:93], v133 offset:18528
	ds_read_b128 v[94:97], v133 offset:23136
	ds_read_b128 v[114:117], v133 offset:27744
	ds_read_b128 v[118:121], v133 offset:32352
	s_waitcnt lgkmcnt(4)
	v_mfma_f32_32x32x16_bf16 v[2:17], v[142:145], v[98:101], v[2:17]
	s_waitcnt lgkmcnt(3)
	v_mfma_f32_32x32x16_bf16 v[50:65], v[90:93], v[102:105], v[50:65]
	s_waitcnt lgkmcnt(2)
	v_mfma_f32_32x32x16_bf16 v[34:49], v[94:97], v[102:105], v[34:49]
	s_waitcnt lgkmcnt(1)
	v_mfma_f32_32x32x16_bf16 v[18:33], v[114:117], v[102:105], v[18:33]
	s_waitcnt lgkmcnt(0)
	v_mfma_f32_32x32x16_bf16 v[2:17], v[118:121], v[102:105], v[2:17]
	s_waitcnt vmcnt(3)
	s_waitcnt lgkmcnt(0)
	s_barrier
	ds_read_b128 v[90:93], v133 offset:36864
	ds_read_b128 v[94:97], v133 offset:41472
	ds_read_b128 v[98:101], v133 offset:46080
	ds_read_b128 v[102:105], v133 offset:50688
	s_waitcnt lgkmcnt(3)
	v_mfma_f32_32x32x16_bf16 v[50:65], v[90:93], v[66:69], v[50:65]
	s_waitcnt lgkmcnt(2)
	v_mfma_f32_32x32x16_bf16 v[34:49], v[94:97], v[66:69], v[34:49]
	s_waitcnt lgkmcnt(1)
	v_mfma_f32_32x32x16_bf16 v[18:33], v[98:101], v[66:69], v[18:33]
	ds_read_b128 v[90:93], v133 offset:36896
	ds_read_b128 v[94:97], v133 offset:41504
	ds_read_b128 v[98:101], v133 offset:46112
	ds_read_b128 v[114:117], v133 offset:50720
	s_waitcnt lgkmcnt(4)
	v_mfma_f32_32x32x16_bf16 v[2:17], v[102:105], v[66:69], v[2:17]
	s_waitcnt lgkmcnt(3)
	v_mfma_f32_32x32x16_bf16 v[50:65], v[90:93], v[70:73], v[50:65]
	s_waitcnt lgkmcnt(2)
	v_mfma_f32_32x32x16_bf16 v[34:49], v[94:97], v[70:73], v[34:49]
	s_waitcnt lgkmcnt(1)
	v_mfma_f32_32x32x16_bf16 v[18:33], v[98:101], v[70:73], v[18:33]
	ds_read_b128 v[66:69], v133 offset:36928
	ds_read_b128 v[90:93], v133 offset:41536
	ds_read_b128 v[94:97], v133 offset:46144
	ds_read_b128 v[98:101], v133 offset:50752
	s_waitcnt lgkmcnt(4)
	v_mfma_f32_32x32x16_bf16 v[2:17], v[114:117], v[70:73], v[2:17]
	s_waitcnt lgkmcnt(3)
	v_mfma_f32_32x32x16_bf16 v[50:65], v[66:69], v[74:77], v[50:65]
	s_waitcnt lgkmcnt(2)
	v_mfma_f32_32x32x16_bf16 v[34:49], v[90:93], v[74:77], v[34:49]
	s_waitcnt lgkmcnt(1)
	v_mfma_f32_32x32x16_bf16 v[18:33], v[94:97], v[74:77], v[18:33]
	ds_read_b128 v[66:69], v133 offset:36960
	ds_read_b128 v[70:73], v133 offset:41568
	ds_read_b128 v[90:93], v133 offset:46176
	ds_read_b128 v[94:97], v133 offset:50784
	s_waitcnt lgkmcnt(4)
	v_mfma_f32_32x32x16_bf16 v[2:17], v[98:101], v[74:77], v[2:17]
	s_waitcnt lgkmcnt(3)
	v_mfma_f32_32x32x16_bf16 v[50:65], v[66:69], v[78:81], v[50:65]
	s_waitcnt lgkmcnt(2)
	v_mfma_f32_32x32x16_bf16 v[34:49], v[70:73], v[78:81], v[34:49]
	s_waitcnt lgkmcnt(1)
	v_mfma_f32_32x32x16_bf16 v[18:33], v[90:93], v[78:81], v[18:33]
	s_waitcnt lgkmcnt(0)
	v_mfma_f32_32x32x16_bf16 v[2:17], v[94:97], v[78:81], v[2:17]
	s_waitcnt vmcnt(0)
	s_waitcnt lgkmcnt(0)
	s_barrier
	ds_read_b128 v[66:69], v133
	ds_read_b128 v[70:73], v133 offset:4608
	ds_read_b128 v[74:77], v133 offset:9216
	ds_read_b128 v[78:81], v133 offset:13824
	s_waitcnt lgkmcnt(3)
	v_mfma_f32_32x32x16_bf16 v[50:65], v[66:69], v[106:109], v[50:65]
	s_waitcnt lgkmcnt(2)
	v_mfma_f32_32x32x16_bf16 v[34:49], v[70:73], v[106:109], v[34:49]
	s_waitcnt lgkmcnt(1)
	v_mfma_f32_32x32x16_bf16 v[18:33], v[74:77], v[106:109], v[18:33]
	ds_read_b128 v[66:69], v133 offset:32
	ds_read_b128 v[70:73], v133 offset:4640
	ds_read_b128 v[74:77], v133 offset:9248
	ds_read_b128 v[82:85], v133 offset:13856
	s_waitcnt lgkmcnt(4)
	v_mfma_f32_32x32x16_bf16 v[2:17], v[78:81], v[106:109], v[2:17]
	s_waitcnt lgkmcnt(3)
	v_mfma_f32_32x32x16_bf16 v[50:65], v[66:69], v[110:113], v[50:65]
	s_waitcnt lgkmcnt(2)
	v_mfma_f32_32x32x16_bf16 v[34:49], v[70:73], v[110:113], v[34:49]
	s_waitcnt lgkmcnt(1)
	v_mfma_f32_32x32x16_bf16 v[18:33], v[74:77], v[110:113], v[18:33]
	ds_read_b128 v[66:69], v133 offset:64
	ds_read_b128 v[70:73], v133 offset:4672
	ds_read_b128 v[74:77], v133 offset:9280
	ds_read_b128 v[78:81], v133 offset:13888
	s_waitcnt lgkmcnt(4)
	v_mfma_f32_32x32x16_bf16 v[2:17], v[82:85], v[110:113], v[2:17]
	s_waitcnt lgkmcnt(3)
	v_mfma_f32_32x32x16_bf16 v[50:65], v[66:69], v[122:125], v[50:65]
	s_waitcnt lgkmcnt(2)
	v_mfma_f32_32x32x16_bf16 v[34:49], v[70:73], v[122:125], v[34:49]
	s_waitcnt lgkmcnt(1)
	v_mfma_f32_32x32x16_bf16 v[18:33], v[74:77], v[122:125], v[18:33]
	ds_read_b128 v[66:69], v133 offset:96
	ds_read_b128 v[70:73], v133 offset:4704
	ds_read_b128 v[74:77], v133 offset:9312
	ds_read_b128 v[82:85], v133 offset:13920
	s_waitcnt lgkmcnt(4)
	v_mfma_f32_32x32x16_bf16 v[2:17], v[78:81], v[122:125], v[2:17]
	s_waitcnt lgkmcnt(3)
	v_mfma_f32_32x32x16_bf16 v[50:65], v[66:69], v[126:129], v[50:65]
	s_waitcnt lgkmcnt(2)
	v_mfma_f32_32x32x16_bf16 v[34:49], v[70:73], v[126:129], v[34:49]
	s_waitcnt lgkmcnt(1)
	v_mfma_f32_32x32x16_bf16 v[18:33], v[74:77], v[126:129], v[18:33]
	s_waitcnt lgkmcnt(0)
	v_mfma_f32_32x32x16_bf16 v[2:17], v[82:85], v[126:129], v[2:17]
	global_load_dwordx2 v[94:95], v[136:137], off offset:256
	global_load_dwordx2 v[96:97], v[136:137], off offset:272
	global_load_dwordx2 v[92:93], v[136:137], off offset:288
	global_load_dwordx2 v[90:91], v[136:137], off offset:304
	global_load_dwordx2 v[88:89], v[136:137], off offset:320
	global_load_dwordx2 v[86:87], v[136:137], off offset:336
	global_load_dwordx2 v[84:85], v[136:137], off offset:352
	global_load_dwordx2 v[82:83], v[136:137], off offset:368
	global_load_dwordx2 v[80:81], v[136:137], off offset:384
	global_load_dwordx2 v[78:79], v[136:137], off offset:400
	global_load_dwordx2 v[76:77], v[136:137], off offset:416
	global_load_dwordx2 v[74:75], v[136:137], off offset:432
	global_load_dwordx2 v[72:73], v[136:137], off offset:448
	global_load_dwordx2 v[70:71], v[136:137], off offset:464
	global_load_dwordx2 v[68:69], v[136:137], off offset:480
	global_load_dwordx2 v[66:67], v[136:137], off offset:496
	v_pk_mul_f32 v[50:51], v[0:1], v[50:51] op_sel_hi:[0,1]
	v_pk_mul_f32 v[52:53], v[0:1], v[52:53] op_sel_hi:[0,1]
	v_pk_mul_f32 v[54:55], v[0:1], v[54:55] op_sel_hi:[0,1]
	v_pk_mul_f32 v[56:57], v[0:1], v[56:57] op_sel_hi:[0,1]
	v_pk_mul_f32 v[34:35], v[0:1], v[34:35] op_sel_hi:[0,1]
	v_pk_mul_f32 v[36:37], v[0:1], v[36:37] op_sel_hi:[0,1]
	v_pk_mul_f32 v[38:39], v[0:1], v[38:39] op_sel_hi:[0,1]
	v_pk_mul_f32 v[40:41], v[0:1], v[40:41] op_sel_hi:[0,1]
	v_pk_mul_f32 v[18:19], v[0:1], v[18:19] op_sel_hi:[0,1]
	v_pk_mul_f32 v[20:21], v[0:1], v[20:21] op_sel_hi:[0,1]
	v_pk_mul_f32 v[22:23], v[0:1], v[22:23] op_sel_hi:[0,1]
	v_pk_mul_f32 v[24:25], v[0:1], v[24:25] op_sel_hi:[0,1]
	v_pk_mul_f32 v[2:3], v[0:1], v[2:3] op_sel_hi:[0,1]
	v_pk_mul_f32 v[4:5], v[0:1], v[4:5] op_sel_hi:[0,1]
	v_pk_mul_f32 v[6:7], v[0:1], v[6:7] op_sel_hi:[0,1]
	v_pk_mul_f32 v[8:9], v[0:1], v[8:9] op_sel_hi:[0,1]
	s_mov_b64 s[0:1], 0
	s_waitcnt vmcnt(15)
	v_lshlrev_b32_e32 v98, 16, v94
	v_and_b32_e32 v99, 0xffff0000, v94
	v_mul_f32_e32 v94, 0xbfb8aa3b, v98
	v_exp_f32_e32 v94, v94
	s_nop 0
	v_add_f32_e32 v94, 1.0, v94
	v_rcp_f32_e32 v100, v94
	v_mul_f32_e32 v94, 0xbfb8aa3b, v99
	v_exp_f32_e32 v94, v94
	s_nop 0
	v_add_f32_e32 v94, 1.0, v94
	v_rcp_f32_e32 v101, v94
	v_lshlrev_b32_e32 v94, 16, v95
	v_and_b32_e32 v95, 0xffff0000, v95
	v_pk_mul_f32 v[98:99], v[100:101], v[98:99]
	s_nop 0
	v_pk_mul_f32 v[50:51], v[50:51], v[98:99]
	s_nop 0
	v_cvt_pk_bf16_f32 v50, v50, v51
	v_mul_f32_e32 v51, 0xbfb8aa3b, v94
	v_exp_f32_e32 v51, v51
	s_nop 0
	v_add_f32_e32 v51, 1.0, v51
	v_rcp_f32_e32 v98, v51
	v_mul_f32_e32 v51, 0xbfb8aa3b, v95
	v_exp_f32_e32 v51, v51
	s_nop 0
	v_add_f32_e32 v51, 1.0, v51
	v_rcp_f32_e32 v99, v51
	s_nop 0
	v_pk_mul_f32 v[94:95], v[98:99], v[94:95]
	s_nop 0
	v_pk_mul_f32 v[52:53], v[52:53], v[94:95]
	s_nop 0
	v_cvt_pk_bf16_f32 v51, v52, v53
	global_store_dwordx2 v[130:131], v[50:51], off offset:256
	s_waitcnt vmcnt(15)
	v_lshlrev_b32_e32 v50, 16, v96
	v_and_b32_e32 v51, 0xffff0000, v96
	v_mul_f32_e32 v52, 0xbfb8aa3b, v50
	v_mul_f32_e32 v53, 0xbfb8aa3b, v51
	v_exp_f32_e32 v52, v52
	v_exp_f32_e32 v53, v53
	v_add_f32_e32 v52, 1.0, v52
	v_add_f32_e32 v53, 1.0, v53
	v_rcp_f32_e32 v52, v52
	v_rcp_f32_e32 v53, v53
	s_nop 0
	v_pk_mul_f32 v[50:51], v[52:53], v[50:51]
	s_nop 0
	v_pk_mul_f32 v[50:51], v[54:55], v[50:51]
	v_lshlrev_b32_e32 v52, 16, v97
	v_cvt_pk_bf16_f32 v50, v50, v51
	v_mul_f32_e32 v51, 0xbfb8aa3b, v52
	v_exp_f32_e32 v51, v51
	v_and_b32_e32 v53, 0xffff0000, v97
	v_add_f32_e32 v51, 1.0, v51
	v_rcp_f32_e32 v54, v51
	v_mul_f32_e32 v51, 0xbfb8aa3b, v53
	v_exp_f32_e32 v51, v51
	s_nop 0
	v_add_f32_e32 v51, 1.0, v51
	v_rcp_f32_e32 v55, v51
	s_nop 0
	v_pk_mul_f32 v[52:53], v[54:55], v[52:53]
	s_nop 0
	v_pk_mul_f32 v[52:53], v[56:57], v[52:53]
	v_pk_mul_f32 v[54:55], v[0:1], v[58:59] op_sel_hi:[0,1]
	v_cvt_pk_bf16_f32 v51, v52, v53
	global_store_dwordx2 v[130:131], v[50:51], off offset:272
	s_waitcnt vmcnt(15)
	v_lshlrev_b32_e32 v50, 16, v92
	v_and_b32_e32 v51, 0xffff0000, v92
	v_mul_f32_e32 v52, 0xbfb8aa3b, v50
	v_mul_f32_e32 v53, 0xbfb8aa3b, v51
	v_exp_f32_e32 v52, v52
	v_exp_f32_e32 v53, v53
	v_pk_mul_f32 v[56:57], v[0:1], v[60:61] op_sel_hi:[0,1]
	v_add_f32_e32 v52, 1.0, v52
	v_add_f32_e32 v53, 1.0, v53
	v_rcp_f32_e32 v52, v52
	v_rcp_f32_e32 v53, v53
	s_nop 0
	v_pk_mul_f32 v[50:51], v[52:53], v[50:51]
	s_nop 0
	v_pk_mul_f32 v[50:51], v[54:55], v[50:51]
	v_lshlrev_b32_e32 v52, 16, v93
	v_cvt_pk_bf16_f32 v50, v50, v51
	v_mul_f32_e32 v51, 0xbfb8aa3b, v52
	v_exp_f32_e32 v51, v51
	v_and_b32_e32 v53, 0xffff0000, v93
	v_add_f32_e32 v51, 1.0, v51
	v_rcp_f32_e32 v54, v51
	v_mul_f32_e32 v51, 0xbfb8aa3b, v53
	v_exp_f32_e32 v51, v51
	s_nop 0
	v_add_f32_e32 v51, 1.0, v51
	v_rcp_f32_e32 v55, v51
	s_nop 0
	v_pk_mul_f32 v[52:53], v[54:55], v[52:53]
	s_nop 0
	v_pk_mul_f32 v[52:53], v[56:57], v[52:53]
	v_pk_mul_f32 v[54:55], v[0:1], v[62:63] op_sel_hi:[0,1]
	v_cvt_pk_bf16_f32 v51, v52, v53
	global_store_dwordx2 v[130:131], v[50:51], off offset:288
	s_waitcnt vmcnt(15)
	v_lshlrev_b32_e32 v50, 16, v90
	v_and_b32_e32 v51, 0xffff0000, v90
	v_mul_f32_e32 v52, 0xbfb8aa3b, v50
	v_mul_f32_e32 v53, 0xbfb8aa3b, v51
	v_exp_f32_e32 v52, v52
	v_exp_f32_e32 v53, v53
	v_pk_mul_f32 v[56:57], v[0:1], v[64:65] op_sel_hi:[0,1]
	v_add_f32_e32 v52, 1.0, v52
	v_add_f32_e32 v53, 1.0, v53
	v_rcp_f32_e32 v52, v52
	v_rcp_f32_e32 v53, v53
	s_nop 0
	v_pk_mul_f32 v[50:51], v[52:53], v[50:51]
	s_nop 0
	v_pk_mul_f32 v[50:51], v[54:55], v[50:51]
	v_lshlrev_b32_e32 v52, 16, v91
	v_cvt_pk_bf16_f32 v50, v50, v51
	v_mul_f32_e32 v51, 0xbfb8aa3b, v52
	v_exp_f32_e32 v51, v51
	v_and_b32_e32 v53, 0xffff0000, v91
	v_add_f32_e32 v51, 1.0, v51
	v_rcp_f32_e32 v54, v51
	v_mul_f32_e32 v51, 0xbfb8aa3b, v53
	v_exp_f32_e32 v51, v51
	s_nop 0
	v_add_f32_e32 v51, 1.0, v51
	v_rcp_f32_e32 v55, v51
	s_nop 0
	v_pk_mul_f32 v[52:53], v[54:55], v[52:53]
	s_nop 0
	v_pk_mul_f32 v[52:53], v[56:57], v[52:53]
	s_nop 0
	v_cvt_pk_bf16_f32 v51, v52, v53
	global_store_dwordx2 v[130:131], v[50:51], off offset:304
	s_waitcnt vmcnt(15)
	v_lshlrev_b32_e32 v50, 16, v88
	v_and_b32_e32 v51, 0xffff0000, v88
	v_mul_f32_e32 v52, 0xbfb8aa3b, v50
	v_mul_f32_e32 v53, 0xbfb8aa3b, v51
	v_exp_f32_e32 v52, v52
	v_exp_f32_e32 v53, v53
	v_add_f32_e32 v52, 1.0, v52
	v_add_f32_e32 v53, 1.0, v53
	v_rcp_f32_e32 v52, v52
	v_rcp_f32_e32 v53, v53
	s_nop 0
	v_pk_mul_f32 v[50:51], v[52:53], v[50:51]
	s_nop 0
	v_pk_mul_f32 v[34:35], v[34:35], v[50:51]
	v_lshlrev_b32_e32 v50, 16, v89
	v_cvt_pk_bf16_f32 v34, v34, v35
	v_mul_f32_e32 v35, 0xbfb8aa3b, v50
	v_exp_f32_e32 v35, v35
	v_and_b32_e32 v51, 0xffff0000, v89
	v_add_f32_e32 v35, 1.0, v35
	v_rcp_f32_e32 v52, v35
	v_mul_f32_e32 v35, 0xbfb8aa3b, v51
	v_exp_f32_e32 v35, v35
	s_nop 0
	v_add_f32_e32 v35, 1.0, v35
	v_rcp_f32_e32 v53, v35
	s_nop 0
	v_pk_mul_f32 v[50:51], v[52:53], v[50:51]
	s_nop 0
	v_pk_mul_f32 v[36:37], v[36:37], v[50:51]
	s_nop 0
	v_cvt_pk_bf16_f32 v35, v36, v37
	global_store_dwordx2 v[130:131], v[34:35], off offset:320
	s_waitcnt vmcnt(15)
	v_lshlrev_b32_e32 v34, 16, v86
	v_and_b32_e32 v35, 0xffff0000, v86
	v_mul_f32_e32 v36, 0xbfb8aa3b, v34
	v_mul_f32_e32 v37, 0xbfb8aa3b, v35
	v_exp_f32_e32 v36, v36
	v_exp_f32_e32 v37, v37
	v_add_f32_e32 v36, 1.0, v36
	v_add_f32_e32 v37, 1.0, v37
	v_rcp_f32_e32 v36, v36
	v_rcp_f32_e32 v37, v37
	s_nop 0
	v_pk_mul_f32 v[34:35], v[36:37], v[34:35]
	s_nop 0
	v_pk_mul_f32 v[34:35], v[38:39], v[34:35]
	v_lshlrev_b32_e32 v36, 16, v87
	v_cvt_pk_bf16_f32 v34, v34, v35
	v_mul_f32_e32 v35, 0xbfb8aa3b, v36
	v_exp_f32_e32 v35, v35
	v_and_b32_e32 v37, 0xffff0000, v87
	v_add_f32_e32 v35, 1.0, v35
	v_rcp_f32_e32 v38, v35
	v_mul_f32_e32 v35, 0xbfb8aa3b, v37
	v_exp_f32_e32 v35, v35
	s_nop 0
	v_add_f32_e32 v35, 1.0, v35
	v_rcp_f32_e32 v39, v35
	s_nop 0
	v_pk_mul_f32 v[36:37], v[38:39], v[36:37]
	s_nop 0
	v_pk_mul_f32 v[36:37], v[40:41], v[36:37]
	v_pk_mul_f32 v[38:39], v[0:1], v[42:43] op_sel_hi:[0,1]
	v_cvt_pk_bf16_f32 v35, v36, v37
	global_store_dwordx2 v[130:131], v[34:35], off offset:336
	s_waitcnt vmcnt(15)
	v_lshlrev_b32_e32 v34, 16, v84
	v_and_b32_e32 v35, 0xffff0000, v84
	v_mul_f32_e32 v36, 0xbfb8aa3b, v34
	v_mul_f32_e32 v37, 0xbfb8aa3b, v35
	v_exp_f32_e32 v36, v36
	v_exp_f32_e32 v37, v37
	v_pk_mul_f32 v[40:41], v[0:1], v[44:45] op_sel_hi:[0,1]
	v_add_f32_e32 v36, 1.0, v36
	v_add_f32_e32 v37, 1.0, v37
	v_rcp_f32_e32 v36, v36
	v_rcp_f32_e32 v37, v37
	s_nop 0
	v_pk_mul_f32 v[34:35], v[36:37], v[34:35]
	s_nop 0
	v_pk_mul_f32 v[34:35], v[38:39], v[34:35]
	v_lshlrev_b32_e32 v36, 16, v85
	v_cvt_pk_bf16_f32 v34, v34, v35
	v_mul_f32_e32 v35, 0xbfb8aa3b, v36
	v_exp_f32_e32 v35, v35
	v_and_b32_e32 v37, 0xffff0000, v85
	v_add_f32_e32 v35, 1.0, v35
	v_rcp_f32_e32 v38, v35
	v_mul_f32_e32 v35, 0xbfb8aa3b, v37
	v_exp_f32_e32 v35, v35
	s_nop 0
	v_add_f32_e32 v35, 1.0, v35
	v_rcp_f32_e32 v39, v35
	s_nop 0
	v_pk_mul_f32 v[36:37], v[38:39], v[36:37]
	s_nop 0
	v_pk_mul_f32 v[36:37], v[40:41], v[36:37]
	v_pk_mul_f32 v[38:39], v[0:1], v[46:47] op_sel_hi:[0,1]
	v_cvt_pk_bf16_f32 v35, v36, v37
	global_store_dwordx2 v[130:131], v[34:35], off offset:352
	s_waitcnt vmcnt(15)
	v_lshlrev_b32_e32 v34, 16, v82
	v_and_b32_e32 v35, 0xffff0000, v82
	v_mul_f32_e32 v36, 0xbfb8aa3b, v34
	v_mul_f32_e32 v37, 0xbfb8aa3b, v35
	v_exp_f32_e32 v36, v36
	v_exp_f32_e32 v37, v37
	v_pk_mul_f32 v[40:41], v[0:1], v[48:49] op_sel_hi:[0,1]
	v_add_f32_e32 v36, 1.0, v36
	v_add_f32_e32 v37, 1.0, v37
	v_rcp_f32_e32 v36, v36
	v_rcp_f32_e32 v37, v37
	s_nop 0
	v_pk_mul_f32 v[34:35], v[36:37], v[34:35]
	s_nop 0
	v_pk_mul_f32 v[34:35], v[38:39], v[34:35]
	v_lshlrev_b32_e32 v36, 16, v83
	v_cvt_pk_bf16_f32 v34, v34, v35
	v_mul_f32_e32 v35, 0xbfb8aa3b, v36
	v_exp_f32_e32 v35, v35
	v_and_b32_e32 v37, 0xffff0000, v83
	v_add_f32_e32 v35, 1.0, v35
	v_rcp_f32_e32 v38, v35
	v_mul_f32_e32 v35, 0xbfb8aa3b, v37
	v_exp_f32_e32 v35, v35
	s_nop 0
	v_add_f32_e32 v35, 1.0, v35
	v_rcp_f32_e32 v39, v35
	s_nop 0
	v_pk_mul_f32 v[36:37], v[38:39], v[36:37]
	s_nop 0
	v_pk_mul_f32 v[36:37], v[40:41], v[36:37]
	s_nop 0
	v_cvt_pk_bf16_f32 v35, v36, v37
	global_store_dwordx2 v[130:131], v[34:35], off offset:368
	s_waitcnt vmcnt(15)
	v_lshlrev_b32_e32 v34, 16, v80
	v_and_b32_e32 v35, 0xffff0000, v80
	v_mul_f32_e32 v36, 0xbfb8aa3b, v34
	v_mul_f32_e32 v37, 0xbfb8aa3b, v35
	v_exp_f32_e32 v36, v36
	v_exp_f32_e32 v37, v37
	v_add_f32_e32 v36, 1.0, v36
	v_add_f32_e32 v37, 1.0, v37
	v_rcp_f32_e32 v36, v36
	v_rcp_f32_e32 v37, v37
	s_nop 0
	v_pk_mul_f32 v[34:35], v[36:37], v[34:35]
	s_nop 0
	v_pk_mul_f32 v[18:19], v[18:19], v[34:35]
	v_lshlrev_b32_e32 v34, 16, v81
	v_cvt_pk_bf16_f32 v18, v18, v19
	v_mul_f32_e32 v19, 0xbfb8aa3b, v34
	v_exp_f32_e32 v19, v19
	v_and_b32_e32 v35, 0xffff0000, v81
	v_add_f32_e32 v19, 1.0, v19
	v_rcp_f32_e32 v36, v19
	v_mul_f32_e32 v19, 0xbfb8aa3b, v35
	v_exp_f32_e32 v19, v19
	s_nop 0
	v_add_f32_e32 v19, 1.0, v19
	v_rcp_f32_e32 v37, v19
	s_nop 0
	v_pk_mul_f32 v[34:35], v[36:37], v[34:35]
	s_nop 0
	v_pk_mul_f32 v[20:21], v[20:21], v[34:35]
	s_nop 0
	v_cvt_pk_bf16_f32 v19, v20, v21
	global_store_dwordx2 v[130:131], v[18:19], off offset:384
	s_waitcnt vmcnt(15)
	v_lshlrev_b32_e32 v18, 16, v78
	v_and_b32_e32 v19, 0xffff0000, v78
	v_mul_f32_e32 v20, 0xbfb8aa3b, v18
	v_mul_f32_e32 v21, 0xbfb8aa3b, v19
	v_exp_f32_e32 v20, v20
	v_exp_f32_e32 v21, v21
	v_add_f32_e32 v20, 1.0, v20
	v_add_f32_e32 v21, 1.0, v21
	v_rcp_f32_e32 v20, v20
	v_rcp_f32_e32 v21, v21
	s_nop 0
	v_pk_mul_f32 v[18:19], v[20:21], v[18:19]
	s_nop 0
	v_pk_mul_f32 v[18:19], v[22:23], v[18:19]
	v_lshlrev_b32_e32 v20, 16, v79
	v_cvt_pk_bf16_f32 v18, v18, v19
	v_mul_f32_e32 v19, 0xbfb8aa3b, v20
	v_exp_f32_e32 v19, v19
	v_and_b32_e32 v21, 0xffff0000, v79
	v_add_f32_e32 v19, 1.0, v19
	v_rcp_f32_e32 v22, v19
	v_mul_f32_e32 v19, 0xbfb8aa3b, v21
	v_exp_f32_e32 v19, v19
	s_nop 0
	v_add_f32_e32 v19, 1.0, v19
	v_rcp_f32_e32 v23, v19
	s_nop 0
	v_pk_mul_f32 v[20:21], v[22:23], v[20:21]
	s_nop 0
	v_pk_mul_f32 v[20:21], v[24:25], v[20:21]
	v_pk_mul_f32 v[22:23], v[0:1], v[26:27] op_sel_hi:[0,1]
	v_cvt_pk_bf16_f32 v19, v20, v21
	global_store_dwordx2 v[130:131], v[18:19], off offset:400
	s_waitcnt vmcnt(15)
	v_lshlrev_b32_e32 v18, 16, v76
	v_and_b32_e32 v19, 0xffff0000, v76
	v_mul_f32_e32 v20, 0xbfb8aa3b, v18
	v_mul_f32_e32 v21, 0xbfb8aa3b, v19
	v_exp_f32_e32 v20, v20
	v_exp_f32_e32 v21, v21
	v_pk_mul_f32 v[24:25], v[0:1], v[28:29] op_sel_hi:[0,1]
	v_add_f32_e32 v20, 1.0, v20
	v_add_f32_e32 v21, 1.0, v21
	v_rcp_f32_e32 v20, v20
	v_rcp_f32_e32 v21, v21
	s_nop 0
	v_pk_mul_f32 v[18:19], v[20:21], v[18:19]
	s_nop 0
	v_pk_mul_f32 v[18:19], v[22:23], v[18:19]
	v_lshlrev_b32_e32 v20, 16, v77
	v_cvt_pk_bf16_f32 v18, v18, v19
	v_mul_f32_e32 v19, 0xbfb8aa3b, v20
	v_exp_f32_e32 v19, v19
	v_and_b32_e32 v21, 0xffff0000, v77
	v_add_f32_e32 v19, 1.0, v19
	v_rcp_f32_e32 v22, v19
	v_mul_f32_e32 v19, 0xbfb8aa3b, v21
	v_exp_f32_e32 v19, v19
	s_nop 0
	v_add_f32_e32 v19, 1.0, v19
	v_rcp_f32_e32 v23, v19
	s_nop 0
	v_pk_mul_f32 v[20:21], v[22:23], v[20:21]
	s_nop 0
	v_pk_mul_f32 v[20:21], v[24:25], v[20:21]
	v_pk_mul_f32 v[22:23], v[0:1], v[30:31] op_sel_hi:[0,1]
	v_cvt_pk_bf16_f32 v19, v20, v21
	global_store_dwordx2 v[130:131], v[18:19], off offset:416
	s_waitcnt vmcnt(15)
	v_lshlrev_b32_e32 v18, 16, v74
	v_and_b32_e32 v19, 0xffff0000, v74
	v_mul_f32_e32 v20, 0xbfb8aa3b, v18
	v_mul_f32_e32 v21, 0xbfb8aa3b, v19
	v_exp_f32_e32 v20, v20
	v_exp_f32_e32 v21, v21
	v_pk_mul_f32 v[24:25], v[0:1], v[32:33] op_sel_hi:[0,1]
	v_add_f32_e32 v20, 1.0, v20
	v_add_f32_e32 v21, 1.0, v21
	v_rcp_f32_e32 v20, v20
	v_rcp_f32_e32 v21, v21
	s_nop 0
	v_pk_mul_f32 v[18:19], v[20:21], v[18:19]
	s_nop 0
	v_pk_mul_f32 v[18:19], v[22:23], v[18:19]
	v_lshlrev_b32_e32 v20, 16, v75
	v_cvt_pk_bf16_f32 v18, v18, v19
	v_mul_f32_e32 v19, 0xbfb8aa3b, v20
	v_exp_f32_e32 v19, v19
	v_and_b32_e32 v21, 0xffff0000, v75
	v_add_f32_e32 v19, 1.0, v19
	v_rcp_f32_e32 v22, v19
	v_mul_f32_e32 v19, 0xbfb8aa3b, v21
	v_exp_f32_e32 v19, v19
	s_nop 0
	v_add_f32_e32 v19, 1.0, v19
	v_rcp_f32_e32 v23, v19
	s_nop 0
	v_pk_mul_f32 v[20:21], v[22:23], v[20:21]
	s_nop 0
	v_pk_mul_f32 v[20:21], v[24:25], v[20:21]
	s_nop 0
	v_cvt_pk_bf16_f32 v19, v20, v21
	global_store_dwordx2 v[130:131], v[18:19], off offset:432
	s_waitcnt vmcnt(15)
	v_lshlrev_b32_e32 v18, 16, v72
	v_and_b32_e32 v19, 0xffff0000, v72
	v_mul_f32_e32 v20, 0xbfb8aa3b, v18
	v_mul_f32_e32 v21, 0xbfb8aa3b, v19
	v_exp_f32_e32 v20, v20
	v_exp_f32_e32 v21, v21
	v_add_f32_e32 v20, 1.0, v20
	v_add_f32_e32 v21, 1.0, v21
	v_rcp_f32_e32 v20, v20
	v_rcp_f32_e32 v21, v21
	s_nop 0
	v_pk_mul_f32 v[18:19], v[20:21], v[18:19]
	s_nop 0
	v_pk_mul_f32 v[2:3], v[2:3], v[18:19]
	v_lshlrev_b32_e32 v18, 16, v73
	v_cvt_pk_bf16_f32 v2, v2, v3
	v_mul_f32_e32 v3, 0xbfb8aa3b, v18
	v_exp_f32_e32 v3, v3
	v_and_b32_e32 v19, 0xffff0000, v73
	v_add_f32_e32 v3, 1.0, v3
	v_rcp_f32_e32 v20, v3
	v_mul_f32_e32 v3, 0xbfb8aa3b, v19
	v_exp_f32_e32 v3, v3
	s_nop 0
	v_add_f32_e32 v3, 1.0, v3
	v_rcp_f32_e32 v21, v3
	s_nop 0
	v_pk_mul_f32 v[18:19], v[20:21], v[18:19]
	s_nop 0
	v_pk_mul_f32 v[4:5], v[4:5], v[18:19]
	s_nop 0
	v_cvt_pk_bf16_f32 v3, v4, v5
	global_store_dwordx2 v[130:131], v[2:3], off offset:448
	s_waitcnt vmcnt(15)
	v_lshlrev_b32_e32 v2, 16, v70
	v_and_b32_e32 v3, 0xffff0000, v70
	v_mul_f32_e32 v4, 0xbfb8aa3b, v2
	v_mul_f32_e32 v5, 0xbfb8aa3b, v3
	v_exp_f32_e32 v4, v4
	v_exp_f32_e32 v5, v5
	v_add_f32_e32 v4, 1.0, v4
	v_add_f32_e32 v5, 1.0, v5
	v_rcp_f32_e32 v4, v4
	v_rcp_f32_e32 v5, v5
	s_nop 0
	v_pk_mul_f32 v[2:3], v[4:5], v[2:3]
	s_nop 0
	v_pk_mul_f32 v[2:3], v[6:7], v[2:3]
	v_lshlrev_b32_e32 v4, 16, v71
	v_cvt_pk_bf16_f32 v2, v2, v3
	v_mul_f32_e32 v3, 0xbfb8aa3b, v4
	v_exp_f32_e32 v3, v3
	v_and_b32_e32 v5, 0xffff0000, v71
	v_add_f32_e32 v3, 1.0, v3
	v_rcp_f32_e32 v6, v3
	v_mul_f32_e32 v3, 0xbfb8aa3b, v5
	v_exp_f32_e32 v3, v3
	s_nop 0
	v_add_f32_e32 v3, 1.0, v3
	v_rcp_f32_e32 v7, v3
	s_nop 0
	v_pk_mul_f32 v[4:5], v[6:7], v[4:5]
	s_nop 0
	v_pk_mul_f32 v[4:5], v[8:9], v[4:5]
	v_pk_mul_f32 v[6:7], v[0:1], v[10:11] op_sel_hi:[0,1]
	v_cvt_pk_bf16_f32 v3, v4, v5
	global_store_dwordx2 v[130:131], v[2:3], off offset:464
	s_waitcnt vmcnt(15)
	v_lshlrev_b32_e32 v2, 16, v68
	v_and_b32_e32 v3, 0xffff0000, v68
	v_mul_f32_e32 v4, 0xbfb8aa3b, v2
	v_mul_f32_e32 v5, 0xbfb8aa3b, v3
	v_exp_f32_e32 v4, v4
	v_exp_f32_e32 v5, v5
	v_pk_mul_f32 v[8:9], v[0:1], v[12:13] op_sel_hi:[0,1]
	v_add_f32_e32 v4, 1.0, v4
	v_add_f32_e32 v5, 1.0, v5
	v_rcp_f32_e32 v4, v4
	v_rcp_f32_e32 v5, v5
	s_nop 0
	v_pk_mul_f32 v[2:3], v[4:5], v[2:3]
	s_nop 0
	v_pk_mul_f32 v[2:3], v[6:7], v[2:3]
	v_lshlrev_b32_e32 v4, 16, v69
	v_cvt_pk_bf16_f32 v2, v2, v3
	v_mul_f32_e32 v3, 0xbfb8aa3b, v4
	v_exp_f32_e32 v3, v3
	v_and_b32_e32 v5, 0xffff0000, v69
	v_add_f32_e32 v3, 1.0, v3
	v_rcp_f32_e32 v6, v3
	v_mul_f32_e32 v3, 0xbfb8aa3b, v5
	v_exp_f32_e32 v3, v3
	s_nop 0
	v_add_f32_e32 v3, 1.0, v3
	v_rcp_f32_e32 v7, v3
	s_nop 0
	v_pk_mul_f32 v[4:5], v[6:7], v[4:5]
	s_nop 0
	v_pk_mul_f32 v[4:5], v[8:9], v[4:5]
	v_pk_mul_f32 v[6:7], v[0:1], v[14:15] op_sel_hi:[0,1]
	v_cvt_pk_bf16_f32 v3, v4, v5
	global_store_dwordx2 v[130:131], v[2:3], off offset:480
	s_waitcnt vmcnt(15)
	v_lshlrev_b32_e32 v2, 16, v66
	v_and_b32_e32 v3, 0xffff0000, v66
	v_mul_f32_e32 v4, 0xbfb8aa3b, v2
	v_mul_f32_e32 v5, 0xbfb8aa3b, v3
	v_exp_f32_e32 v4, v4
	v_exp_f32_e32 v5, v5
	v_pk_mul_f32 v[8:9], v[0:1], v[16:17] op_sel_hi:[0,1]
	v_add_f32_e32 v4, 1.0, v4
	v_add_f32_e32 v5, 1.0, v5
	v_rcp_f32_e32 v4, v4
	v_rcp_f32_e32 v5, v5
	s_nop 0
	v_pk_mul_f32 v[2:3], v[4:5], v[2:3]
	s_nop 0
	v_pk_mul_f32 v[2:3], v[6:7], v[2:3]
	v_lshlrev_b32_e32 v4, 16, v67
	v_and_b32_e32 v5, 0xffff0000, v67
	v_cvt_pk_bf16_f32 v2, v2, v3
	v_mul_f32_e32 v3, 0xbfb8aa3b, v4
	v_mul_f32_e32 v0, 0xbfb8aa3b, v5
	v_exp_f32_e32 v3, v3
	v_exp_f32_e32 v0, v0
	v_add_f32_e32 v3, 1.0, v3
	v_add_f32_e32 v0, 1.0, v0
	v_rcp_f32_e32 v6, v3
	v_rcp_f32_e32 v7, v0
	s_nop 0
	v_pk_mul_f32 v[4:5], v[6:7], v[4:5]
	s_nop 0
	v_pk_mul_f32 v[4:5], v[8:9], v[4:5]
	s_nop 0
	v_cvt_pk_bf16_f32 v3, v4, v5
	global_store_dwordx2 v[130:131], v[2:3], off offset:496
	s_barrier
